# GLU/out-proj/gate-up/down stores written through at agent scope; the group-local syncs after them skip the L2 write-back (nothing of theirs is left dirty)
# baseline (speedup 1.0000x reference)
; __device__ __forceinline__ unsigned pk2(float lo, float hi) { return pg8::cvt_pk_bf16(lo, hi); }
; __device__ __forceinline__ float sigmoidf_(float x) { return __builtin_amdgcn_rcpf(1.f + fexp(-x)); }
;     __device__ __forceinline__ void operator()(const f32x4 (&acc)[2][2][4][2], const pg8::Unit& u, int wr, int wc, int fr, int fq) const {
;         const int row0 = u.pm * 256 + wr * 64 + fr;
;         const int j0 = u.pn * 128 + wc * 32 + 8 * fq;
;         f32x4 ba[2], bb[2];
; #pragma unroll
;         for (int bj = 0; bj < 2; ++bj) { ba[bj] = *(const f32x4*)(bias + j0 + 4 * bj); bb[bj] = *(const f32x4*)(bias + DSSM + j0 + 4 * bj); }
; #pragma unroll
;         for (int ai = 0; ai < 2; ++ai)
; #pragma unroll
;             for (int m = 0; m < 4; ++m) {
;                 const int r = row0 + ai * 128 + m * 16;
;                 float o[2][4];
; #pragma unroll
;                 for (int bj = 0; bj < 2; ++bj) { const f32x4 a = acc[ai][bj][m][0] + ba[bj], b = acc[ai][bj][m][1] + bb[bj];
; #pragma unroll
;                     for (int i = 0; i < 4; ++i) o[bj][i] = a[i] * sigmoidf_(b[i]); }
;                 u32x4 w; w.x = pk2(o[0][0], o[0][1]); w.y = pk2(o[0][2], o[0][3]); w.z = pk2(o[1][0], o[1][1]); w.w = pk2(o[1][2], o[1][3]);
;                 *(u32x4*)(MIX + (size_t)r * DM + j0) = w;
;             }
.LBB0_1318:
	v_lshl_or_b32 v158, s1, 7, v188
	v_ashrrev_i32_e32 v159, 31, v158
	v_lshlrev_b64 v[72:73], 2, v[158:159]
	v_lshl_add_u64 v[74:75], s[12:13], 0, v[72:73]
	global_load_dwordx4 v[88:91], v[74:75], off
	v_lshl_add_u64 v[72:73], s[8:9], 0, v[72:73]
	global_load_dwordx4 v[92:95], v[72:73], off
	global_load_dwordx4 v[76:79], v[74:75], off offset:16
	s_nop 0
	global_load_dwordx4 v[72:75], v[72:73], off offset:16
	v_lshl_add_u32 v160, s0, 8, v164
	v_ashrrev_i32_e32 v161, 31, v160
	v_lshlrev_b64 v[150:151], 12, v[160:161]
	v_lshlrev_b64 v[162:163], 1, v[158:159]
	v_lshl_add_u64 v[150:151], s[6:7], 0, v[150:151]
	v_lshl_add_u64 v[158:159], v[150:151], 0, v[162:163]
	s_mov_b32 s0, 0x80000
	s_waitcnt vmcnt(0)
	v_pk_add_f32 v[60:61], v[60:61], v[92:93]
	v_add_f32_e32 v56, v56, v88
	v_add_f32_e32 v57, v57, v89
	v_mul_f32_e32 v56, 0xbfb8aa3b, v56
	v_mul_f32_e32 v57, 0xbfb8aa3b, v57
	v_exp_f32_e32 v56, v56
	v_exp_f32_e32 v57, v57
	v_add_f32_e32 v40, v40, v88
	v_add_f32_e32 v41, v41, v89
	v_mul_f32_e32 v40, 0xbfb8aa3b, v40
	v_mul_f32_e32 v41, 0xbfb8aa3b, v41
	v_exp_f32_e32 v40, v40
	v_exp_f32_e32 v41, v41
	v_add_f32_e32 v24, v24, v88
	v_add_f32_e32 v25, v25, v89
	v_mul_f32_e32 v24, 0xbfb8aa3b, v24
	v_mul_f32_e32 v25, 0xbfb8aa3b, v25
	v_add_f32_e32 v104, v104, v88
	v_add_f32_e32 v105, v105, v89
	v_add_f32_e32 v80, v80, v88
	v_add_f32_e32 v81, v81, v89
	v_add_f32_e32 v56, 1.0, v56
	v_add_f32_e32 v57, 1.0, v57
	v_add_f32_e32 v58, v58, v90
	v_add_f32_e32 v59, v59, v91
	v_exp_f32_e32 v24, v24
	v_exp_f32_e32 v25, v25
	v_add_f32_e32 v8, v8, v88
	v_add_f32_e32 v9, v9, v89
	v_mul_f32_e32 v104, 0xbfb8aa3b, v104
	v_mul_f32_e32 v105, 0xbfb8aa3b, v105
	v_mul_f32_e32 v80, 0xbfb8aa3b, v80
	v_mul_f32_e32 v81, 0xbfb8aa3b, v81
	v_rcp_f32_e32 v56, v56
	v_rcp_f32_e32 v57, v57
	v_mul_f32_e32 v58, 0xbfb8aa3b, v58
	v_mul_f32_e32 v59, 0xbfb8aa3b, v59
	v_mul_f32_e32 v8, 0xbfb8aa3b, v8
	v_mul_f32_e32 v9, 0xbfb8aa3b, v9
	v_exp_f32_e32 v104, v104
	v_exp_f32_e32 v105, v105
	v_exp_f32_e32 v80, v80
	v_exp_f32_e32 v81, v81
	v_exp_f32_e32 v58, v58
	v_exp_f32_e32 v59, v59
	v_add_f32_e32 v40, 1.0, v40
	v_add_f32_e32 v41, 1.0, v41
	v_add_f32_e32 v42, v42, v90
	v_add_f32_e32 v43, v43, v91
	v_exp_f32_e32 v8, v8
	v_exp_f32_e32 v9, v9
	v_add_f32_e32 v52, v52, v76
	v_rcp_f32_e32 v40, v40
	v_rcp_f32_e32 v41, v41
	v_mul_f32_e32 v42, 0xbfb8aa3b, v42
	v_mul_f32_e32 v43, 0xbfb8aa3b, v43
	v_add_f32_e32 v150, v136, v88
	v_add_f32_e32 v151, v137, v89
	v_mul_f32_e32 v52, 0xbfb8aa3b, v52
	v_exp_f32_e32 v42, v42
	v_exp_f32_e32 v43, v43
	v_add_f32_e32 v24, 1.0, v24
	v_add_f32_e32 v25, 1.0, v25
	v_add_f32_e32 v26, v26, v90
	v_add_f32_e32 v27, v27, v91
	v_pk_add_f32 v[136:137], v[142:143], v[94:95]
	v_add_f32_e32 v138, v138, v90
	v_add_f32_e32 v139, v139, v91
	v_add_f32_e32 v142, v128, v76
	v_add_f32_e32 v143, v129, v77
	v_pk_add_f32 v[128:129], v[134:135], v[74:75]
	v_add_f32_e32 v130, v130, v78
	v_add_f32_e32 v131, v131, v79
	v_add_f32_e32 v134, v120, v88
	v_add_f32_e32 v135, v121, v89
	v_pk_add_f32 v[120:121], v[126:127], v[94:95]
	v_add_f32_e32 v122, v122, v90
	v_add_f32_e32 v123, v123, v91
	v_mul_f32_e32 v126, 0xbfb8aa3b, v150
	v_mul_f32_e32 v127, 0xbfb8aa3b, v151
	v_pk_mul_f32 v[56:57], v[60:61], v[56:57]
	v_exp_f32_e32 v60, v52
	v_add_f32_e32 v52, v53, v77
	v_add_f32_e32 v36, v36, v76
	v_rcp_f32_e32 v24, v24
	v_rcp_f32_e32 v25, v25
	v_mul_f32_e32 v26, 0xbfb8aa3b, v26
	v_mul_f32_e32 v27, 0xbfb8aa3b, v27
	v_mul_f32_e32 v138, 0xbfb8aa3b, v138
	v_mul_f32_e32 v139, 0xbfb8aa3b, v139
	v_mul_f32_e32 v142, 0xbfb8aa3b, v142
	v_mul_f32_e32 v143, 0xbfb8aa3b, v143
	v_mul_f32_e32 v130, 0xbfb8aa3b, v130
	v_mul_f32_e32 v131, 0xbfb8aa3b, v131
	v_mul_f32_e32 v122, 0xbfb8aa3b, v122
	v_mul_f32_e32 v123, 0xbfb8aa3b, v123
	v_exp_f32_e32 v126, v126
	v_exp_f32_e32 v127, v127
	v_add_f32_e32 v104, 1.0, v104
	v_add_f32_e32 v105, 1.0, v105
	v_add_f32_e32 v106, v106, v90
	v_add_f32_e32 v107, v107, v91
	v_add_f32_e32 v80, 1.0, v80
	v_add_f32_e32 v81, 1.0, v81
	v_add_f32_e32 v82, v82, v90
	v_add_f32_e32 v83, v83, v91
	v_add_f32_e32 v58, 1.0, v58
	v_add_f32_e32 v59, 1.0, v59
	v_mul_f32_e32 v52, 0xbfb8aa3b, v52
	v_pk_add_f32 v[44:45], v[44:45], v[92:93]
	v_mul_f32_e32 v36, 0xbfb8aa3b, v36
	v_exp_f32_e32 v26, v26
	v_exp_f32_e32 v27, v27
	v_add_f32_e32 v8, 1.0, v8
	v_add_f32_e32 v9, 1.0, v9
	v_add_f32_e32 v10, v10, v90
	v_add_f32_e32 v11, v11, v91
	v_exp_f32_e32 v138, v138
	v_exp_f32_e32 v139, v139
	v_exp_f32_e32 v142, v142
	v_exp_f32_e32 v143, v143
	v_exp_f32_e32 v130, v130
	v_exp_f32_e32 v131, v131
	v_exp_f32_e32 v122, v122
	v_exp_f32_e32 v123, v123
	v_rcp_f32_e32 v104, v104
	v_rcp_f32_e32 v105, v105
	v_mul_f32_e32 v106, 0xbfb8aa3b, v106
	v_mul_f32_e32 v107, 0xbfb8aa3b, v107
	v_rcp_f32_e32 v80, v80
	v_rcp_f32_e32 v81, v81
	v_mul_f32_e32 v82, 0xbfb8aa3b, v82
	v_mul_f32_e32 v83, 0xbfb8aa3b, v83
	v_rcp_f32_e32 v58, v58
	v_rcp_f32_e32 v59, v59
	v_exp_f32_e32 v61, v52
	v_pk_mul_f32 v[40:41], v[44:45], v[40:41]
	v_exp_f32_e32 v44, v36
	v_add_f32_e32 v36, v37, v77
	v_add_f32_e32 v20, v20, v76
	v_rcp_f32_e32 v8, v8
	v_rcp_f32_e32 v9, v9
	v_mul_f32_e32 v10, 0xbfb8aa3b, v10
	v_mul_f32_e32 v11, 0xbfb8aa3b, v11
	v_add_f32_e32 v116, v116, v76
	v_add_f32_e32 v117, v117, v77
	v_exp_f32_e32 v106, v106
	v_exp_f32_e32 v107, v107
	v_exp_f32_e32 v82, v82
	v_exp_f32_e32 v83, v83
	v_add_f32_e32 v42, 1.0, v42
	v_add_f32_e32 v43, 1.0, v43
	v_mul_f32_e32 v36, 0xbfb8aa3b, v36
	v_pk_add_f32 v[28:29], v[28:29], v[92:93]
	v_mul_f32_e32 v20, 0xbfb8aa3b, v20
	v_exp_f32_e32 v10, v10
	v_exp_f32_e32 v11, v11
	v_mul_f32_e32 v116, 0xbfb8aa3b, v116
	v_mul_f32_e32 v117, 0xbfb8aa3b, v117
	v_add_f32_e32 v100, v100, v76
	v_add_f32_e32 v68, v68, v76
; __device__ __forceinline__ unsigned pk2(float lo, float hi) { return pg8::cvt_pk_bf16(lo, hi); }
; __device__ __forceinline__ float sigmoidf_(float x) { return __builtin_amdgcn_rcpf(1.f + fexp(-x)); }
;     __device__ __forceinline__ void operator()(const f32x4 (&acc)[2][2][4][2], const pg8::Unit& u, int wr, int wc, int fr, int fq) const {
;     ...
;                 for (int bj = 0; bj < 2; ++bj) { const f32x4 a = acc[ai][bj][m][0] + ba[bj], b = acc[ai][bj][m][1] + bb[bj];
; #pragma unroll
;                     for (int i = 0; i < 4; ++i) o[bj][i] = a[i] * sigmoidf_(b[i]); }
;                 u32x4 w; w.x = pk2(o[0][0], o[0][1]); w.y = pk2(o[0][2], o[0][3]); w.z = pk2(o[1][0], o[1][1]); w.w = pk2(o[1][2], o[1][3]);
	v_rcp_f32_e32 v42, v42
	v_rcp_f32_e32 v43, v43
	v_exp_f32_e32 v45, v36
	v_pk_mul_f32 v[24:25], v[28:29], v[24:25]
	v_exp_f32_e32 v28, v20
	v_add_f32_e32 v20, v21, v77
	v_add_f32_e32 v4, v4, v76
	v_exp_f32_e32 v150, v116
	v_exp_f32_e32 v151, v117
	v_add_f32_e32 v116, 1.0, v126
	v_add_f32_e32 v117, 1.0, v127
	v_pk_add_f32 v[108:109], v[108:109], v[92:93]
	v_mul_f32_e32 v100, 0xbfb8aa3b, v100
	v_pk_add_f32 v[84:85], v[84:85], v[92:93]
	v_mul_f32_e32 v68, 0xbfb8aa3b, v68
	v_pk_add_f32 v[62:63], v[62:63], v[94:95]
	v_add_f32_e32 v26, 1.0, v26
	v_add_f32_e32 v27, 1.0, v27
	v_mul_f32_e32 v20, 0xbfb8aa3b, v20
	v_pk_add_f32 v[12:13], v[12:13], v[92:93]
	v_mul_f32_e32 v4, 0xbfb8aa3b, v4
	v_add_f32_e32 v126, 1.0, v138
	v_add_f32_e32 v127, 1.0, v139
	v_add_f32_e32 v138, 1.0, v142
	v_add_f32_e32 v139, 1.0, v143
	v_add_f32_e32 v130, 1.0, v130
	v_add_f32_e32 v131, 1.0, v131
	v_add_f32_e32 v142, 1.0, v122
	v_add_f32_e32 v143, 1.0, v123
	v_rcp_f32_e32 v116, v116
	v_rcp_f32_e32 v117, v117
	v_add_f32_e32 v118, v118, v78
	v_add_f32_e32 v119, v119, v79
	v_pk_mul_f32 v[104:105], v[108:109], v[104:105]
	v_exp_f32_e32 v108, v100
	v_add_f32_e32 v100, v101, v77
	v_pk_mul_f32 v[80:81], v[84:85], v[80:81]
	v_exp_f32_e32 v84, v68
	v_add_f32_e32 v68, v69, v77
	v_pk_mul_f32 v[52:53], v[62:63], v[58:59]
	v_add_f32_e32 v58, 1.0, v60
	v_add_f32_e32 v59, 1.0, v61
	v_rcp_f32_e32 v26, v26
	v_rcp_f32_e32 v27, v27
	v_exp_f32_e32 v29, v20
	v_pk_mul_f32 v[8:9], v[12:13], v[8:9]
	v_exp_f32_e32 v12, v4
	v_add_f32_e32 v4, v5, v77
	v_rcp_f32_e32 v122, v126
	v_rcp_f32_e32 v123, v127
	v_rcp_f32_e32 v126, v138
	v_rcp_f32_e32 v127, v139
	v_rcp_f32_e32 v130, v130
	v_rcp_f32_e32 v131, v131
	v_rcp_f32_e32 v138, v142
	v_rcp_f32_e32 v139, v143
	v_mul_f32_e32 v118, 0xbfb8aa3b, v118
	v_mul_f32_e32 v119, 0xbfb8aa3b, v119
	v_add_f32_e32 v106, 1.0, v106
	v_add_f32_e32 v107, 1.0, v107
	v_mul_f32_e32 v100, 0xbfb8aa3b, v100
	v_add_f32_e32 v102, v102, v78
	v_add_f32_e32 v103, v103, v79
	v_add_f32_e32 v82, 1.0, v82
	v_add_f32_e32 v83, 1.0, v83
	v_mul_f32_e32 v68, 0xbfb8aa3b, v68
	v_add_f32_e32 v70, v70, v78
	v_add_f32_e32 v71, v71, v79
	v_rcp_f32_e32 v58, v58
	v_add_f32_e32 v54, v54, v78
	v_add_f32_e32 v55, v55, v79
	v_rcp_f32_e32 v59, v59
	v_pk_add_f32 v[46:47], v[46:47], v[94:95]
	v_add_f32_e32 v38, v38, v78
	v_add_f32_e32 v39, v39, v79
	v_add_f32_e32 v22, v22, v78
	v_add_f32_e32 v23, v23, v79
	v_add_f32_e32 v10, 1.0, v10
	v_add_f32_e32 v11, 1.0, v11
	v_mul_f32_e32 v4, 0xbfb8aa3b, v4
	v_add_f32_e32 v6, v6, v78
	v_add_f32_e32 v7, v7, v79
	v_mul_f32_e32 v134, 0xbfb8aa3b, v134
	v_mul_f32_e32 v135, 0xbfb8aa3b, v135
	v_exp_f32_e32 v118, v118
	v_exp_f32_e32 v119, v119
	v_rcp_f32_e32 v106, v106
	v_rcp_f32_e32 v107, v107
	v_exp_f32_e32 v109, v100
	v_mul_f32_e32 v102, 0xbfb8aa3b, v102
	v_mul_f32_e32 v103, 0xbfb8aa3b, v103
	v_rcp_f32_e32 v82, v82
	v_rcp_f32_e32 v83, v83
	v_exp_f32_e32 v85, v68
	v_mul_f32_e32 v70, 0xbfb8aa3b, v70
	v_mul_f32_e32 v71, 0xbfb8aa3b, v71
	v_mul_f32_e32 v54, 0xbfb8aa3b, v54
	v_mul_f32_e32 v55, 0xbfb8aa3b, v55
	v_pk_mul_f32 v[36:37], v[46:47], v[42:43]
	v_add_f32_e32 v42, 1.0, v44
	v_add_f32_e32 v43, 1.0, v45
	v_mul_f32_e32 v38, 0xbfb8aa3b, v38
	v_mul_f32_e32 v39, 0xbfb8aa3b, v39
	v_mul_f32_e32 v22, 0xbfb8aa3b, v22
	v_mul_f32_e32 v23, 0xbfb8aa3b, v23
	v_rcp_f32_e32 v10, v10
	v_rcp_f32_e32 v11, v11
	v_exp_f32_e32 v13, v4
	v_mul_f32_e32 v6, 0xbfb8aa3b, v6
	v_mul_f32_e32 v7, 0xbfb8aa3b, v7
	v_pk_add_f32 v[140:141], v[140:141], v[92:93]
	v_exp_f32_e32 v134, v134
	v_exp_f32_e32 v135, v135
	v_exp_f32_e32 v102, v102
	v_exp_f32_e32 v103, v103
	v_exp_f32_e32 v70, v70
	v_exp_f32_e32 v71, v71
	v_exp_f32_e32 v54, v54
	v_exp_f32_e32 v55, v55
	v_rcp_f32_e32 v42, v42
	v_exp_f32_e32 v38, v38
	v_exp_f32_e32 v39, v39
	v_rcp_f32_e32 v43, v43
	v_pk_add_f32 v[30:31], v[30:31], v[94:95]
	v_exp_f32_e32 v22, v22
	v_exp_f32_e32 v23, v23
	v_exp_f32_e32 v6, v6
	v_exp_f32_e32 v7, v7
	v_pk_mul_f32 v[116:117], v[140:141], v[116:117]
	v_pk_add_f32 v[48:49], v[48:49], v[72:73]
	v_pk_mul_f32 v[20:21], v[30:31], v[26:27]
	v_add_f32_e32 v26, 1.0, v28
	v_add_f32_e32 v27, 1.0, v29
	v_pk_mul_f32 v[128:129], v[128:129], v[130:131]
	v_pk_mul_f32 v[130:131], v[120:121], v[138:139]
	v_cvt_pk_bf16_f32 v120, v116, v117
	v_add_f32_e32 v116, 1.0, v150
	v_add_f32_e32 v117, 1.0, v151
	v_pk_add_f32 v[110:111], v[110:111], v[94:95]
	v_pk_add_f32 v[86:87], v[86:87], v[94:95]
	v_pk_mul_f32 v[58:59], v[48:49], v[58:59]
	v_cvt_pk_bf16_f32 v49, v52, v53
	v_add_co_u32_e32 v52, vcc, s0, v158
	v_rcp_f32_e32 v26, v26
	v_rcp_f32_e32 v27, v27
	v_pk_add_f32 v[14:15], v[14:15], v[94:95]
	v_pk_add_f32 v[132:133], v[132:133], v[72:73]
	v_rcp_f32_e32 v116, v116
	v_rcp_f32_e32 v117, v117
	v_add_f32_e32 v118, 1.0, v118
	v_add_f32_e32 v119, 1.0, v119
	v_pk_mul_f32 v[100:101], v[110:111], v[106:107]
	v_add_f32_e32 v106, 1.0, v108
	v_add_f32_e32 v107, 1.0, v109
	v_pk_mul_f32 v[68:69], v[86:87], v[82:83]
	v_add_f32_e32 v82, 1.0, v84
; __device__ __forceinline__ unsigned pk2(float lo, float hi) { return pg8::cvt_pk_bf16(lo, hi); }
; __device__ __forceinline__ float sigmoidf_(float x) { return __builtin_amdgcn_rcpf(1.f + fexp(-x)); }
;     __device__ __forceinline__ void operator()(const f32x4 (&acc)[2][2][4][2], const pg8::Unit& u, int wr, int wc, int fr, int fq) const {
;     ...
;                 for (int bj = 0; bj < 2; ++bj) { const f32x4 a = acc[ai][bj][m][0] + ba[bj], b = acc[ai][bj][m][1] + bb[bj];
; #pragma unroll
;                     for (int i = 0; i < 4; ++i) o[bj][i] = a[i] * sigmoidf_(b[i]); }
;                 u32x4 w; w.x = pk2(o[0][0], o[0][1]); w.y = pk2(o[0][2], o[0][3]); w.z = pk2(o[1][0], o[1][1]); w.w = pk2(o[1][2], o[1][3]);
;                 *(u32x4*)(MIX + (size_t)r * DM + j0) = w;
	v_add_f32_e32 v83, 1.0, v85
	v_addc_co_u32_e32 v53, vcc, 0, v159, vcc
	v_pk_add_f32 v[32:33], v[32:33], v[72:73]
	s_mov_b32 s0, 0x90000
	v_pk_mul_f32 v[4:5], v[14:15], v[10:11]
	v_add_f32_e32 v10, 1.0, v12
	v_add_f32_e32 v11, 1.0, v13
	v_add_f32_e32 v134, 1.0, v134
	v_add_f32_e32 v135, 1.0, v135
	v_pk_mul_f32 v[122:123], v[136:137], v[122:123]
	v_pk_mul_f32 v[126:127], v[132:133], v[126:127]
	v_rcp_f32_e32 v118, v118
	v_rcp_f32_e32 v119, v119
	v_rcp_f32_e32 v106, v106
	v_rcp_f32_e32 v107, v107
	v_add_f32_e32 v102, 1.0, v102
	v_add_f32_e32 v103, 1.0, v103
	v_rcp_f32_e32 v82, v82
	v_rcp_f32_e32 v83, v83
	v_add_f32_e32 v70, 1.0, v70
	v_add_f32_e32 v71, 1.0, v71
	v_add_f32_e32 v54, 1.0, v54
	v_add_f32_e32 v55, 1.0, v55
	v_add_f32_e32 v38, 1.0, v38
	v_add_f32_e32 v39, 1.0, v39
	v_pk_mul_f32 v[42:43], v[32:33], v[42:43]
	v_cvt_pk_bf16_f32 v33, v36, v37
	v_add_co_u32_e32 v36, vcc, s0, v158
	v_add_f32_e32 v22, 1.0, v22
	v_add_f32_e32 v23, 1.0, v23
	v_rcp_f32_e32 v10, v10
	v_rcp_f32_e32 v11, v11
	v_add_f32_e32 v6, 1.0, v6
	v_add_f32_e32 v7, 1.0, v7
	v_rcp_f32_e32 v134, v134
	v_rcp_f32_e32 v135, v135
	v_cvt_pk_bf16_f32 v121, v122, v123
	v_cvt_pk_bf16_f32 v122, v126, v127
	v_cvt_pk_bf16_f32 v123, v128, v129
	v_rcp_f32_e32 v102, v102
	v_rcp_f32_e32 v103, v103
	v_rcp_f32_e32 v70, v70
	v_rcp_f32_e32 v71, v71
	v_rcp_f32_e32 v54, v54
	v_rcp_f32_e32 v55, v55
	v_rcp_f32_e32 v38, v38
	v_rcp_f32_e32 v39, v39
	v_addc_co_u32_e32 v37, vcc, 0, v159, vcc
	v_rcp_f32_e32 v22, v22
	v_rcp_f32_e32 v23, v23
	v_pk_add_f32 v[16:17], v[16:17], v[72:73]
	s_mov_b32 s0, 0xa0000
	v_rcp_f32_e32 v6, v6
	v_rcp_f32_e32 v7, v7
	global_store_dwordx4 v[158:159], v[120:123], off sc1
	v_pk_add_f32 v[112:113], v[112:113], v[72:73]
	v_or_b32_e32 v108, 32, v160
	v_or_b32_e32 v120, 16, v160
	v_or_b32_e32 v84, 48, v160
	v_pk_mul_f32 v[26:27], v[16:17], v[26:27]
	v_cvt_pk_bf16_f32 v17, v20, v21
	v_add_co_u32_e32 v20, vcc, s0, v158
	v_pk_add_f32 v[114:115], v[114:115], v[74:75]
	v_pk_mul_f32 v[116:117], v[112:113], v[116:117]
	v_ashrrev_i32_e32 v121, 31, v120
	v_pk_add_f32 v[96:97], v[96:97], v[72:73]
	v_ashrrev_i32_e32 v109, 31, v108
	v_pk_add_f32 v[64:65], v[64:65], v[72:73]
	v_ashrrev_i32_e32 v85, 31, v84
	v_addc_co_u32_e32 v21, vcc, 0, v159, vcc
	v_pk_add_f32 v[0:1], v[0:1], v[72:73]
	v_pk_add_f32 v[124:125], v[124:125], v[92:93]
	v_pk_mul_f32 v[118:119], v[114:115], v[118:119]
	v_cvt_pk_bf16_f32 v114, v116, v117
	v_lshlrev_b64 v[116:117], 12, v[120:121]
	v_pk_add_f32 v[98:99], v[98:99], v[74:75]
	v_pk_mul_f32 v[106:107], v[96:97], v[106:107]
	v_cvt_pk_bf16_f32 v97, v100, v101
	v_lshlrev_b64 v[100:101], 12, v[108:109]
	v_pk_add_f32 v[66:67], v[66:67], v[74:75]
	v_pk_mul_f32 v[82:83], v[64:65], v[82:83]
	v_cvt_pk_bf16_f32 v65, v68, v69
	v_lshlrev_b64 v[68:69], 12, v[84:85]
	v_pk_add_f32 v[50:51], v[50:51], v[74:75]
	v_pk_add_f32 v[34:35], v[34:35], v[74:75]
	v_pk_add_f32 v[18:19], v[18:19], v[74:75]
	v_pk_add_f32 v[2:3], v[2:3], v[74:75]
	v_pk_mul_f32 v[10:11], v[0:1], v[10:11]
	v_cvt_pk_bf16_f32 v1, v4, v5
	v_add_co_u32_e32 v4, vcc, 0xb0000, v158
	v_pk_mul_f32 v[124:125], v[124:125], v[134:135]
	v_lshl_add_u64 v[116:117], s[6:7], 0, v[116:117]
	v_pk_mul_f32 v[102:103], v[98:99], v[102:103]
	v_lshl_add_u64 v[100:101], s[6:7], 0, v[100:101]
	v_pk_mul_f32 v[70:71], v[66:67], v[70:71]
	v_lshl_add_u64 v[68:69], s[6:7], 0, v[68:69]
	v_pk_mul_f32 v[54:55], v[50:51], v[54:55]
	v_pk_mul_f32 v[38:39], v[34:35], v[38:39]
	v_pk_mul_f32 v[22:23], v[18:19], v[22:23]
	v_pk_mul_f32 v[6:7], v[2:3], v[6:7]
	v_addc_co_u32_e32 v5, vcc, 0, v159, vcc
	v_cvt_pk_bf16_f32 v112, v124, v125
	v_cvt_pk_bf16_f32 v113, v130, v131
	v_cvt_pk_bf16_f32 v115, v118, v119
	v_lshl_add_u64 v[116:117], v[116:117], 0, v[162:163]
	v_cvt_pk_bf16_f32 v96, v104, v105
	v_cvt_pk_bf16_f32 v98, v106, v107
	v_cvt_pk_bf16_f32 v99, v102, v103
	v_lshl_add_u64 v[100:101], v[100:101], 0, v[162:163]
	v_cvt_pk_bf16_f32 v64, v80, v81
	v_cvt_pk_bf16_f32 v66, v82, v83
	v_cvt_pk_bf16_f32 v67, v70, v71
	v_lshl_add_u64 v[68:69], v[68:69], 0, v[162:163]
	v_cvt_pk_bf16_f32 v48, v56, v57
	v_cvt_pk_bf16_f32 v50, v58, v59
	v_cvt_pk_bf16_f32 v51, v54, v55
	v_cvt_pk_bf16_f32 v32, v40, v41
	v_cvt_pk_bf16_f32 v34, v42, v43
	v_cvt_pk_bf16_f32 v35, v38, v39
	v_cvt_pk_bf16_f32 v16, v24, v25
	v_cvt_pk_bf16_f32 v18, v26, v27
	v_cvt_pk_bf16_f32 v19, v22, v23
	v_cvt_pk_bf16_f32 v0, v8, v9
	v_cvt_pk_bf16_f32 v2, v10, v11
	v_cvt_pk_bf16_f32 v3, v6, v7
	s_andn2_b64 vcc, exec, s[2:3]
	s_mov_b64 s[0:1], -1
	global_store_dwordx4 v[116:117], v[112:115], off sc1
	global_store_dwordx4 v[100:101], v[96:99], off sc1
	global_store_dwordx4 v[68:69], v[64:67], off sc1
	global_store_dwordx4 v[52:53], v[48:51], off sc1
	global_store_dwordx4 v[36:37], v[32:35], off sc1
	global_store_dwordx4 v[20:21], v[16:19], off sc1
	global_store_dwordx4 v[4:5], v[0:3], off sc1
	s_cbranch_vccnz .LBB0_1307
	s_andn2_b64 vcc, exec, s[4:5]
	s_cbranch_vccnz .LBB0_1306
	s_barrier
	s_branch .LBB0_1306

.LBB0_1322:
	s_waitcnt vmcnt(0) lgkmcnt(0)
	s_barrier
	v_mbcnt_lo_u32_b32 v0, -1, 0
	v_mbcnt_hi_u32_b32 v0, -1, v0
	s_nop 0
	v_cmp_eq_u32_e32 vcc, 0, v0
	s_and_b64 s[2:3], s[92:93], vcc
	s_and_saveexec_b64 s[0:1], s[2:3]
	v_readlane_b32 s12, v254, 15
	v_readlane_b32 s13, v254, 16
	s_cbranch_execz .LBB0_1336
	s_mov_b64 s[2:3], s[68:69]
	s_load_dwordx2 s[2:3], s[2:3], 0xd8
	s_mov_b64 s[4:5], exec
	s_nop 0
	s_waitcnt vmcnt(0) lgkmcnt(0)
	s_waitcnt vmcnt(0)
	v_mbcnt_lo_u32_b32 v0, s4, 0
	v_mbcnt_hi_u32_b32 v0, s5, v0
	v_cmp_eq_u32_e32 vcc, 0, v0
	s_and_saveexec_b64 s[6:7], vcc
	s_cbranch_execz .LBB0_1325
	s_bcnt1_i32_b64 s4, s[4:5]
	v_mov_b32_e32 v0, s4
	s_and_b32 s4, s76, 7
	s_lshl_b32 s4, s4, 6
	s_add_i32 s4, s4, 0x400
	s_add_u32 s4, s2, s4
	s_addc_u32 s5, s3, 0
	global_atomic_add v145, v0, s[4:5]

; __device__ __forceinline__ unsigned pk2(float lo, float hi) { return pg8::cvt_pk_bf16(lo, hi); }
; __device__ __forceinline__ float bflo(unsigned w) { return __uint_as_float(w << 16); }
; __device__ __forceinline__ float bfhi(unsigned w) { return __uint_as_float(w & 0xffff0000u); }
;     __device__ __forceinline__ void operator()(const f32x4 (&acc)[2][2][4][2], const pg8::Unit& u, int wr, int wc, int fr, int fq) const {
;         const int row0 = u.pm * 256 + wr * 64 + fr; const int col0 = u.pn * 256 + wc * 32 + 8 * fq;
; #pragma unroll
;         for (int ai = 0; ai < 2; ++ai)
; #pragma unroll
;             for (int m = 0; m < 4; ++m) {
;                 const int r = row0 + ai * 128 + m * 16; float ss = 0.f;
; #pragma unroll
;                 for (int bj = 0; bj < 2; ++bj) {
;                     const size_t off = (size_t)r * DM + col0 + bj * 128;
;                     const u32x4 old = *(const u32x4*)(XB + off);
;                     const f32x4 x0 = (f32x4){bflo(old.x), bfhi(old.x), bflo(old.y), bfhi(old.y)} + acc[ai][bj][m][0];
;                     const f32x4 x1 = (f32x4){bflo(old.z), bfhi(old.z), bflo(old.w), bfhi(old.w)} + acc[ai][bj][m][1];
;                     u32x4 w; w.x = pk2(x0[0], x0[1]); w.y = pk2(x0[2], x0[3]); w.z = pk2(x1[0], x1[1]); w.w = pk2(x1[2], x1[3]); *(u32x4*)(XB + off) = w;
;                     ss += ((x0[0] * x0[0] + x0[1] * x0[1]) + (x0[2] * x0[2] + x0[3] * x0[3])) + ((x1[0] * x1[0] + x1[1] * x1[1]) + (x1[2] * x1[2] + x1[3] * x1[3]));
;                 }
;                 ss += __shfl_xor(ss, 16); ss += __shfl_xor(ss, 32);
;                 if (fq == 0) rowsq[(size_t)(u.pn * 4 + wc) * MTOK + r] = ss;
;             }
;     }
.LBB0_1358:
	v_lshl_add_u32 v134, s20, 8, v140
	v_ashrrev_i32_e32 v135, 31, v134
	v_lshl_or_b32 v138, s0, 8, v142
	v_lshlrev_b64 v[136:137], 12, v[134:135]
	v_ashrrev_i32_e32 v139, 31, v138
	v_lshl_add_u64 v[136:137], s[8:9], 0, v[136:137]
	v_lshl_add_u64 v[136:137], v[138:139], 1, v[136:137]
	global_load_dwordx4 v[154:157], v[136:137], off
	global_load_dwordx4 v[158:161], v[136:137], off offset:256
	v_xor_b32_e32 v150, 16, v170
	v_xor_b32_e32 v151, 32, v170
	v_cmp_lt_i32_e32 vcc, v150, v171
	s_lshl_b32 s0, s0, 2
	s_or_b32 s0, s0, s45
	v_cndmask_b32_e32 v150, v170, v150, vcc
	v_cmp_lt_i32_e32 vcc, v151, v171
	v_lshlrev_b32_e32 v153, 2, v150
	s_ashr_i32 s1, s0, 31
	v_cndmask_b32_e32 v151, v170, v151, vcc
	v_lshlrev_b32_e32 v152, 2, v151
	s_lshl_b64 s[20:21], s[0:1], 16
	s_waitcnt vmcnt(0)
	v_lshlrev_b32_e32 v150, 16, v154
	v_and_b32_e32 v151, 0xffff0000, v154
	v_lshlrev_b32_e32 v154, 16, v155
	v_and_b32_e32 v155, 0xffff0000, v155
	v_lshlrev_b32_e32 v162, 16, v156
	v_and_b32_e32 v163, 0xffff0000, v156
	v_lshlrev_b32_e32 v156, 16, v157
	v_and_b32_e32 v157, 0xffff0000, v157
	v_lshlrev_b32_e32 v164, 16, v158
	v_and_b32_e32 v165, 0xffff0000, v158
	v_lshlrev_b32_e32 v158, 16, v159
	v_and_b32_e32 v159, 0xffff0000, v159
	v_lshlrev_b32_e32 v188, 16, v160
	v_and_b32_e32 v189, 0xffff0000, v160
	v_lshlrev_b32_e32 v160, 16, v161
	v_and_b32_e32 v161, 0xffff0000, v161
	v_pk_add_f32 v[126:127], v[126:127], v[154:155]
	v_pk_add_f32 v[124:125], v[124:125], v[150:151]
	v_pk_add_f32 v[122:123], v[122:123], v[156:157]
	v_pk_add_f32 v[120:121], v[120:121], v[162:163]
	v_pk_add_f32 v[118:119], v[118:119], v[158:159]
	v_pk_add_f32 v[116:117], v[116:117], v[164:165]
	v_pk_add_f32 v[150:151], v[114:115], v[160:161]
	v_pk_add_f32 v[154:155], v[112:113], v[188:189]
	v_cvt_pk_bf16_f32 v112, v124, v125
	v_cvt_pk_bf16_f32 v113, v126, v127
	v_mul_f32_e32 v114, v125, v125
	v_mul_f32_e32 v115, v127, v127
	v_mul_f32_e32 v125, v121, v121
	v_mul_f32_e32 v127, v123, v123
	v_mul_f32_e32 v156, v117, v117
	v_mul_f32_e32 v157, v119, v119
	v_mul_f32_e32 v158, v155, v155
	v_mul_f32_e32 v159, v151, v151
	v_fmac_f32_e32 v114, v124, v124
	v_fmac_f32_e32 v115, v126, v126
	v_fmac_f32_e32 v125, v120, v120
	v_fmac_f32_e32 v127, v122, v122
	v_fmac_f32_e32 v156, v116, v116
	v_fmac_f32_e32 v157, v118, v118
	v_fmac_f32_e32 v158, v154, v154
	v_fmac_f32_e32 v159, v150, v150
	v_add_f32_e32 v114, v114, v115
	v_add_f32_e32 v115, v125, v127
	v_add_f32_e32 v124, v156, v157
	v_add_f32_e32 v125, v158, v159
	v_add_f32_e32 v114, v114, v115
	v_add_f32_e32 v115, v124, v125
	v_add_f32_e32 v124, v114, v115
	ds_bpermute_b32 v125, v153, v124
	v_cvt_pk_bf16_f32 v114, v120, v121
	v_cvt_pk_bf16_f32 v115, v122, v123
	global_store_dwordx4 v[136:137], v[112:115], off sc1
	s_waitcnt lgkmcnt(0)
	s_nop 0
	v_add_f32_e32 v112, v124, v125
	ds_bpermute_b32 v113, v152, v112
	v_cvt_pk_bf16_f32 v114, v116, v117
	v_cvt_pk_bf16_f32 v115, v118, v119
	v_cvt_pk_bf16_f32 v116, v154, v155
	v_cvt_pk_bf16_f32 v117, v150, v151
	global_store_dwordx4 v[136:137], v[114:117], off offset:256 sc1
	s_and_saveexec_b64 s[0:1], s[2:3]
	s_cbranch_execz .LBB0_1360
	s_add_u32 s22, s43, s20
	s_addc_u32 s23, s44, s21
	s_waitcnt lgkmcnt(0)
	v_add_f32_e32 v114, v112, v113
	v_lshl_add_u64 v[112:113], v[134:135], 2, s[22:23]
	global_store_dword v[112:113], v114, off sc1
.LBB0_1360:
	s_or_b64 exec, exec, s[0:1]
	v_or_b32_e32 v112, 16, v134
	s_waitcnt lgkmcnt(0)
	v_ashrrev_i32_e32 v113, 31, v112
	v_lshlrev_b64 v[112:113], 12, v[112:113]
	v_lshl_add_u64 v[112:113], s[8:9], 0, v[112:113]
	v_lshl_add_u64 v[112:113], v[138:139], 1, v[112:113]
	global_load_dwordx4 v[114:117], v[112:113], off
	global_load_dwordx4 v[118:121], v[112:113], off offset:256
	s_waitcnt vmcnt(1)
	v_lshlrev_b32_e32 v122, 16, v114
	v_and_b32_e32 v123, 0xffff0000, v114
	v_lshlrev_b32_e32 v114, 16, v115
	v_and_b32_e32 v115, 0xffff0000, v115
	v_lshlrev_b32_e32 v124, 16, v116
	v_and_b32_e32 v125, 0xffff0000, v116
	v_lshlrev_b32_e32 v116, 16, v117
	v_and_b32_e32 v117, 0xffff0000, v117
	s_waitcnt vmcnt(0)
	v_lshlrev_b32_e32 v126, 16, v118
	v_and_b32_e32 v127, 0xffff0000, v118
	v_lshlrev_b32_e32 v118, 16, v119
	v_and_b32_e32 v119, 0xffff0000, v119
	v_lshlrev_b32_e32 v150, 16, v120
	v_and_b32_e32 v151, 0xffff0000, v120
	v_lshlrev_b32_e32 v120, 16, v121
	v_and_b32_e32 v121, 0xffff0000, v121
	v_pk_add_f32 v[110:111], v[110:111], v[114:115]
	v_pk_add_f32 v[108:109], v[108:109], v[122:123]
	v_pk_add_f32 v[106:107], v[106:107], v[116:117]
	v_pk_add_f32 v[104:105], v[104:105], v[124:125]
	v_pk_add_f32 v[102:103], v[102:103], v[118:119]
	v_pk_add_f32 v[100:101], v[100:101], v[126:127]
	v_pk_add_f32 v[114:115], v[98:99], v[120:121]
	v_pk_add_f32 v[116:117], v[96:97], v[150:151]
	v_cvt_pk_bf16_f32 v96, v108, v109
	v_cvt_pk_bf16_f32 v97, v110, v111
	v_mul_f32_e32 v98, v109, v109
	v_mul_f32_e32 v99, v111, v111
	v_mul_f32_e32 v109, v105, v105
	v_mul_f32_e32 v111, v107, v107
	v_mul_f32_e32 v118, v101, v101
	v_mul_f32_e32 v119, v103, v103
	v_mul_f32_e32 v120, v117, v117
	v_mul_f32_e32 v121, v115, v115
	v_fmac_f32_e32 v98, v108, v108
	v_fmac_f32_e32 v99, v110, v110
	v_fmac_f32_e32 v109, v104, v104
	v_fmac_f32_e32 v111, v106, v106
	v_fmac_f32_e32 v118, v100, v100
	v_fmac_f32_e32 v119, v102, v102
	v_fmac_f32_e32 v120, v116, v116
	v_fmac_f32_e32 v121, v114, v114
	v_add_f32_e32 v98, v98, v99
	v_add_f32_e32 v99, v109, v111
	v_add_f32_e32 v108, v118, v119
	v_add_f32_e32 v109, v120, v121
	v_add_f32_e32 v98, v98, v99
	v_add_f32_e32 v99, v108, v109
	v_add_f32_e32 v108, v98, v99
	ds_bpermute_b32 v109, v153, v108
	v_cvt_pk_bf16_f32 v98, v104, v105
	v_cvt_pk_bf16_f32 v99, v106, v107
	global_store_dwordx4 v[112:113], v[96:99], off sc1
	s_waitcnt lgkmcnt(0)
	s_nop 0
	v_add_f32_e32 v96, v108, v109
	ds_bpermute_b32 v97, v152, v96
	v_cvt_pk_bf16_f32 v98, v100, v101
	v_cvt_pk_bf16_f32 v99, v102, v103
	v_cvt_pk_bf16_f32 v100, v116, v117
	v_cvt_pk_bf16_f32 v101, v114, v115
	global_store_dwordx4 v[112:113], v[98:101], off offset:256 sc1
	s_and_saveexec_b64 s[0:1], s[2:3]
	s_cbranch_execz .LBB0_1362
	s_add_u32 s22, s43, s20
	s_addc_u32 s23, s44, s21
	s_waitcnt lgkmcnt(0)
	v_add_f32_e32 v98, v96, v97
	v_lshl_add_u64 v[96:97], v[134:135], 2, s[22:23]
	global_store_dword v[96:97], v98, off offset:64 sc1
; __device__ __forceinline__ unsigned pk2(float lo, float hi) { return pg8::cvt_pk_bf16(lo, hi); }
; __device__ __forceinline__ float bflo(unsigned w) { return __uint_as_float(w << 16); }
; __device__ __forceinline__ float bfhi(unsigned w) { return __uint_as_float(w & 0xffff0000u); }
;     __device__ __forceinline__ void operator()(const f32x4 (&acc)[2][2][4][2], const pg8::Unit& u, int wr, int wc, int fr, int fq) const {
;         const int row0 = u.pm * 256 + wr * 64 + fr; const int col0 = u.pn * 256 + wc * 32 + 8 * fq;
; #pragma unroll
;         for (int ai = 0; ai < 2; ++ai)
; #pragma unroll
;             for (int m = 0; m < 4; ++m) {
;                 const int r = row0 + ai * 128 + m * 16; float ss = 0.f;
; #pragma unroll
;                 for (int bj = 0; bj < 2; ++bj) {
;                     const size_t off = (size_t)r * DM + col0 + bj * 128;
;                     const u32x4 old = *(const u32x4*)(XB + off);
;                     const f32x4 x0 = (f32x4){bflo(old.x), bfhi(old.x), bflo(old.y), bfhi(old.y)} + acc[ai][bj][m][0];
;                     const f32x4 x1 = (f32x4){bflo(old.z), bfhi(old.z), bflo(old.w), bfhi(old.w)} + acc[ai][bj][m][1];
;                     u32x4 w; w.x = pk2(x0[0], x0[1]); w.y = pk2(x0[2], x0[3]); w.z = pk2(x1[0], x1[1]); w.w = pk2(x1[2], x1[3]); *(u32x4*)(XB + off) = w;
;                     ss += ((x0[0] * x0[0] + x0[1] * x0[1]) + (x0[2] * x0[2] + x0[3] * x0[3])) + ((x1[0] * x1[0] + x1[1] * x1[1]) + (x1[2] * x1[2] + x1[3] * x1[3]));
;                 }
;                 ss += __shfl_xor(ss, 16); ss += __shfl_xor(ss, 32);
;                 if (fq == 0) rowsq[(size_t)(u.pn * 4 + wc) * MTOK + r] = ss;
;             }
;     }
.LBB0_1362:
	s_or_b64 exec, exec, s[0:1]
	v_or_b32_e32 v96, 32, v134
	s_waitcnt lgkmcnt(0)
	v_ashrrev_i32_e32 v97, 31, v96
	v_lshlrev_b64 v[96:97], 12, v[96:97]
	v_lshl_add_u64 v[96:97], s[8:9], 0, v[96:97]
	v_lshl_add_u64 v[96:97], v[138:139], 1, v[96:97]
	global_load_dwordx4 v[98:101], v[96:97], off
	global_load_dwordx4 v[102:105], v[96:97], off offset:256
	s_waitcnt vmcnt(1)
	v_lshlrev_b32_e32 v106, 16, v98
	v_and_b32_e32 v107, 0xffff0000, v98
	v_lshlrev_b32_e32 v98, 16, v99
	v_and_b32_e32 v99, 0xffff0000, v99
	v_lshlrev_b32_e32 v108, 16, v100
	v_and_b32_e32 v109, 0xffff0000, v100
	v_lshlrev_b32_e32 v100, 16, v101
	v_and_b32_e32 v101, 0xffff0000, v101
	s_waitcnt vmcnt(0)
	v_lshlrev_b32_e32 v110, 16, v102
	v_and_b32_e32 v111, 0xffff0000, v102
	v_lshlrev_b32_e32 v102, 16, v103
	v_and_b32_e32 v103, 0xffff0000, v103
	v_lshlrev_b32_e32 v112, 16, v104
	v_and_b32_e32 v113, 0xffff0000, v104
	v_lshlrev_b32_e32 v104, 16, v105
	v_and_b32_e32 v105, 0xffff0000, v105
	v_pk_add_f32 v[94:95], v[94:95], v[98:99]
	v_pk_add_f32 v[92:93], v[92:93], v[106:107]
	v_pk_add_f32 v[90:91], v[90:91], v[100:101]
	v_pk_add_f32 v[88:89], v[88:89], v[108:109]
	v_pk_add_f32 v[86:87], v[86:87], v[102:103]
	v_pk_add_f32 v[84:85], v[84:85], v[110:111]
	v_pk_add_f32 v[98:99], v[82:83], v[104:105]
	v_pk_add_f32 v[100:101], v[80:81], v[112:113]
	v_cvt_pk_bf16_f32 v80, v92, v93
	v_cvt_pk_bf16_f32 v81, v94, v95
	v_mul_f32_e32 v82, v93, v93
	v_mul_f32_e32 v83, v95, v95
	v_mul_f32_e32 v93, v89, v89
	v_mul_f32_e32 v95, v91, v91
	v_mul_f32_e32 v102, v85, v85
	v_mul_f32_e32 v103, v87, v87
	v_mul_f32_e32 v104, v101, v101
	v_mul_f32_e32 v105, v99, v99
	v_fmac_f32_e32 v82, v92, v92
	v_fmac_f32_e32 v83, v94, v94
	v_fmac_f32_e32 v93, v88, v88
	v_fmac_f32_e32 v95, v90, v90
	v_fmac_f32_e32 v102, v84, v84
	v_fmac_f32_e32 v103, v86, v86
	v_fmac_f32_e32 v104, v100, v100
	v_fmac_f32_e32 v105, v98, v98
	v_add_f32_e32 v82, v82, v83
	v_add_f32_e32 v83, v93, v95
	v_add_f32_e32 v92, v102, v103
	v_add_f32_e32 v93, v104, v105
	v_add_f32_e32 v82, v82, v83
	v_add_f32_e32 v83, v92, v93
	v_add_f32_e32 v92, v82, v83
	ds_bpermute_b32 v93, v153, v92
	v_cvt_pk_bf16_f32 v82, v88, v89
	v_cvt_pk_bf16_f32 v83, v90, v91
	global_store_dwordx4 v[96:97], v[80:83], off sc1
	s_waitcnt lgkmcnt(0)
	s_nop 0
	v_add_f32_e32 v80, v92, v93
	ds_bpermute_b32 v81, v152, v80
	v_cvt_pk_bf16_f32 v82, v84, v85
	v_cvt_pk_bf16_f32 v83, v86, v87
	v_cvt_pk_bf16_f32 v84, v100, v101
	v_cvt_pk_bf16_f32 v85, v98, v99
	global_store_dwordx4 v[96:97], v[82:85], off offset:256 sc1
	s_and_saveexec_b64 s[0:1], s[2:3]
	s_cbranch_execz .LBB0_1364
	s_add_u32 s22, s43, s20
	s_addc_u32 s23, s44, s21
	s_waitcnt lgkmcnt(0)
	v_add_f32_e32 v82, v80, v81
	v_lshl_add_u64 v[80:81], v[134:135], 2, s[22:23]
	global_store_dword v[80:81], v82, off offset:128 sc1
.LBB0_1364:
	s_or_b64 exec, exec, s[0:1]
	v_or_b32_e32 v80, 48, v134
	s_waitcnt lgkmcnt(0)
	v_ashrrev_i32_e32 v81, 31, v80
	v_lshlrev_b64 v[80:81], 12, v[80:81]
	v_lshl_add_u64 v[80:81], s[8:9], 0, v[80:81]
	v_lshl_add_u64 v[80:81], v[138:139], 1, v[80:81]
	global_load_dwordx4 v[82:85], v[80:81], off
	global_load_dwordx4 v[86:89], v[80:81], off offset:256
	s_waitcnt vmcnt(1)
	v_lshlrev_b32_e32 v90, 16, v82
	v_and_b32_e32 v91, 0xffff0000, v82
	v_lshlrev_b32_e32 v82, 16, v83
	v_and_b32_e32 v83, 0xffff0000, v83
	v_lshlrev_b32_e32 v92, 16, v84
	v_and_b32_e32 v93, 0xffff0000, v84
	v_lshlrev_b32_e32 v84, 16, v85
	v_and_b32_e32 v85, 0xffff0000, v85
	s_waitcnt vmcnt(0)
	v_lshlrev_b32_e32 v94, 16, v86
	v_and_b32_e32 v95, 0xffff0000, v86
	v_lshlrev_b32_e32 v86, 16, v87
	v_and_b32_e32 v87, 0xffff0000, v87
	v_lshlrev_b32_e32 v96, 16, v88
	v_and_b32_e32 v97, 0xffff0000, v88
	v_lshlrev_b32_e32 v88, 16, v89
	v_and_b32_e32 v89, 0xffff0000, v89
	v_pk_add_f32 v[78:79], v[78:79], v[82:83]
	v_pk_add_f32 v[76:77], v[76:77], v[90:91]
	v_pk_add_f32 v[74:75], v[74:75], v[84:85]
	v_pk_add_f32 v[72:73], v[72:73], v[92:93]
	v_pk_add_f32 v[70:71], v[70:71], v[86:87]
	v_pk_add_f32 v[68:69], v[68:69], v[94:95]
	v_pk_add_f32 v[82:83], v[66:67], v[88:89]
	v_pk_add_f32 v[84:85], v[64:65], v[96:97]
	v_cvt_pk_bf16_f32 v64, v76, v77
	v_cvt_pk_bf16_f32 v65, v78, v79
	v_mul_f32_e32 v66, v77, v77
	v_mul_f32_e32 v67, v79, v79
	v_mul_f32_e32 v77, v73, v73
	v_mul_f32_e32 v79, v75, v75
	v_mul_f32_e32 v86, v69, v69
	v_mul_f32_e32 v87, v71, v71
	v_mul_f32_e32 v88, v85, v85
	v_mul_f32_e32 v89, v83, v83
	v_fmac_f32_e32 v66, v76, v76
	v_fmac_f32_e32 v67, v78, v78
	v_fmac_f32_e32 v77, v72, v72
	v_fmac_f32_e32 v79, v74, v74
	v_fmac_f32_e32 v86, v68, v68
	v_fmac_f32_e32 v87, v70, v70
	v_fmac_f32_e32 v88, v84, v84
	v_fmac_f32_e32 v89, v82, v82
	v_add_f32_e32 v66, v66, v67
	v_add_f32_e32 v67, v77, v79
	v_add_f32_e32 v76, v86, v87
	v_add_f32_e32 v77, v88, v89
	v_add_f32_e32 v66, v66, v67
	v_add_f32_e32 v67, v76, v77
	v_add_f32_e32 v76, v66, v67
	ds_bpermute_b32 v77, v153, v76
	v_cvt_pk_bf16_f32 v66, v72, v73
	v_cvt_pk_bf16_f32 v67, v74, v75
	global_store_dwordx4 v[80:81], v[64:67], off sc1
	s_waitcnt lgkmcnt(0)
	s_nop 0
	v_add_f32_e32 v64, v76, v77
	ds_bpermute_b32 v65, v152, v64
	v_cvt_pk_bf16_f32 v66, v68, v69
	v_cvt_pk_bf16_f32 v67, v70, v71
	v_cvt_pk_bf16_f32 v68, v84, v85
	v_cvt_pk_bf16_f32 v69, v82, v83
	global_store_dwordx4 v[80:81], v[66:69], off offset:256 sc1
	s_and_saveexec_b64 s[0:1], s[2:3]
	s_cbranch_execz .LBB0_1366
	s_add_u32 s22, s43, s20
	s_addc_u32 s23, s44, s21
	s_waitcnt lgkmcnt(0)
	v_add_f32_e32 v66, v64, v65
	v_lshl_add_u64 v[64:65], v[134:135], 2, s[22:23]
	global_store_dword v[64:65], v66, off offset:192 sc1
; __device__ __forceinline__ unsigned pk2(float lo, float hi) { return pg8::cvt_pk_bf16(lo, hi); }
; __device__ __forceinline__ float bflo(unsigned w) { return __uint_as_float(w << 16); }
; __device__ __forceinline__ float bfhi(unsigned w) { return __uint_as_float(w & 0xffff0000u); }
;     __device__ __forceinline__ void operator()(const f32x4 (&acc)[2][2][4][2], const pg8::Unit& u, int wr, int wc, int fr, int fq) const {
;         const int row0 = u.pm * 256 + wr * 64 + fr; const int col0 = u.pn * 256 + wc * 32 + 8 * fq;
; #pragma unroll
;         for (int ai = 0; ai < 2; ++ai)
; #pragma unroll
;             for (int m = 0; m < 4; ++m) {
;                 const int r = row0 + ai * 128 + m * 16; float ss = 0.f;
; #pragma unroll
;                 for (int bj = 0; bj < 2; ++bj) {
;                     const size_t off = (size_t)r * DM + col0 + bj * 128;
;                     const u32x4 old = *(const u32x4*)(XB + off);
;                     const f32x4 x0 = (f32x4){bflo(old.x), bfhi(old.x), bflo(old.y), bfhi(old.y)} + acc[ai][bj][m][0];
;                     const f32x4 x1 = (f32x4){bflo(old.z), bfhi(old.z), bflo(old.w), bfhi(old.w)} + acc[ai][bj][m][1];
;                     u32x4 w; w.x = pk2(x0[0], x0[1]); w.y = pk2(x0[2], x0[3]); w.z = pk2(x1[0], x1[1]); w.w = pk2(x1[2], x1[3]); *(u32x4*)(XB + off) = w;
;                     ss += ((x0[0] * x0[0] + x0[1] * x0[1]) + (x0[2] * x0[2] + x0[3] * x0[3])) + ((x1[0] * x1[0] + x1[1] * x1[1]) + (x1[2] * x1[2] + x1[3] * x1[3]));
;                 }
;                 ss += __shfl_xor(ss, 16); ss += __shfl_xor(ss, 32);
;                 if (fq == 0) rowsq[(size_t)(u.pn * 4 + wc) * MTOK + r] = ss;
;             }
;     }
.LBB0_1366:
	s_or_b64 exec, exec, s[0:1]
	v_add_co_u32_e32 v66, vcc, 0x80000, v136
	s_waitcnt lgkmcnt(0)
	v_lshl_add_u64 v[64:65], v[136:137], 0, s[94:95]
	v_addc_co_u32_e32 v67, vcc, 0, v137, vcc
	global_load_dwordx4 v[68:71], v[66:67], off
	global_load_dwordx4 v[72:75], v[64:65], off offset:256
	s_waitcnt vmcnt(1)
	v_lshlrev_b32_e32 v76, 16, v68
	v_and_b32_e32 v77, 0xffff0000, v68
	v_lshlrev_b32_e32 v68, 16, v69
	v_and_b32_e32 v69, 0xffff0000, v69
	v_lshlrev_b32_e32 v78, 16, v70
	v_and_b32_e32 v79, 0xffff0000, v70
	v_lshlrev_b32_e32 v70, 16, v71
	v_and_b32_e32 v71, 0xffff0000, v71
	s_waitcnt vmcnt(0)
	v_lshlrev_b32_e32 v80, 16, v72
	v_and_b32_e32 v81, 0xffff0000, v72
	v_lshlrev_b32_e32 v72, 16, v73
	v_and_b32_e32 v73, 0xffff0000, v73
	v_lshlrev_b32_e32 v82, 16, v74
	v_and_b32_e32 v83, 0xffff0000, v74
	v_lshlrev_b32_e32 v74, 16, v75
	v_and_b32_e32 v75, 0xffff0000, v75
	v_pk_add_f32 v[62:63], v[62:63], v[68:69]
	v_pk_add_f32 v[60:61], v[60:61], v[76:77]
	v_pk_add_f32 v[58:59], v[58:59], v[70:71]
	v_pk_add_f32 v[56:57], v[56:57], v[78:79]
	v_pk_add_f32 v[54:55], v[54:55], v[72:73]
	v_pk_add_f32 v[52:53], v[52:53], v[80:81]
	v_pk_add_f32 v[68:69], v[50:51], v[74:75]
	v_pk_add_f32 v[70:71], v[48:49], v[82:83]
	v_cvt_pk_bf16_f32 v48, v60, v61
	v_cvt_pk_bf16_f32 v49, v62, v63
	v_mul_f32_e32 v50, v61, v61
	v_mul_f32_e32 v51, v63, v63
	v_mul_f32_e32 v61, v57, v57
	v_mul_f32_e32 v63, v59, v59
	v_mul_f32_e32 v72, v53, v53
	v_mul_f32_e32 v73, v55, v55
	v_mul_f32_e32 v74, v71, v71
	v_mul_f32_e32 v75, v69, v69
	v_fmac_f32_e32 v50, v60, v60
	v_fmac_f32_e32 v51, v62, v62
	v_fmac_f32_e32 v61, v56, v56
	v_fmac_f32_e32 v63, v58, v58
	v_fmac_f32_e32 v72, v52, v52
	v_fmac_f32_e32 v73, v54, v54
	v_fmac_f32_e32 v74, v70, v70
	v_fmac_f32_e32 v75, v68, v68
	v_add_f32_e32 v50, v50, v51
	v_add_f32_e32 v51, v61, v63
	v_add_f32_e32 v60, v72, v73
	v_add_f32_e32 v61, v74, v75
	v_add_f32_e32 v50, v50, v51
	v_add_f32_e32 v51, v60, v61
	v_add_f32_e32 v60, v50, v51
	ds_bpermute_b32 v61, v153, v60
	v_cvt_pk_bf16_f32 v50, v56, v57
	v_cvt_pk_bf16_f32 v51, v58, v59
	global_store_dwordx4 v[66:67], v[48:51], off sc1
	s_waitcnt lgkmcnt(0)
	s_nop 0
	v_add_f32_e32 v48, v60, v61
	ds_bpermute_b32 v49, v152, v48
	v_cvt_pk_bf16_f32 v50, v52, v53
	v_cvt_pk_bf16_f32 v51, v54, v55
	v_cvt_pk_bf16_f32 v52, v70, v71
	v_cvt_pk_bf16_f32 v53, v68, v69
	global_store_dwordx4 v[64:65], v[50:53], off offset:256 sc1
	s_and_saveexec_b64 s[0:1], s[2:3]
	s_cbranch_execz .LBB0_1368
	s_add_u32 s22, s43, s20
	s_addc_u32 s23, s44, s21
	s_waitcnt lgkmcnt(0)
	v_add_f32_e32 v50, v48, v49
	v_lshl_add_u64 v[48:49], v[134:135], 2, s[22:23]
	global_store_dword v[48:49], v50, off offset:512 sc1
.LBB0_1368:
	s_or_b64 exec, exec, s[0:1]
	v_add_co_u32_e32 v50, vcc, 0x90000, v136
	s_mov_b64 s[0:1], 0x90000
	s_nop 0
	v_addc_co_u32_e32 v51, vcc, 0, v137, vcc
	s_waitcnt lgkmcnt(0)
	v_lshl_add_u64 v[48:49], v[136:137], 0, s[0:1]
	global_load_dwordx4 v[52:55], v[50:51], off
	global_load_dwordx4 v[56:59], v[48:49], off offset:256
	s_waitcnt vmcnt(1)
	v_lshlrev_b32_e32 v60, 16, v52
	v_and_b32_e32 v61, 0xffff0000, v52
	v_lshlrev_b32_e32 v52, 16, v53
	v_and_b32_e32 v53, 0xffff0000, v53
	v_lshlrev_b32_e32 v62, 16, v54
	v_and_b32_e32 v63, 0xffff0000, v54
	v_lshlrev_b32_e32 v54, 16, v55
	v_and_b32_e32 v55, 0xffff0000, v55
	s_waitcnt vmcnt(0)
	v_lshlrev_b32_e32 v64, 16, v56
	v_and_b32_e32 v65, 0xffff0000, v56
	v_lshlrev_b32_e32 v56, 16, v57
	v_and_b32_e32 v57, 0xffff0000, v57
	v_lshlrev_b32_e32 v66, 16, v58
	v_and_b32_e32 v67, 0xffff0000, v58
	v_lshlrev_b32_e32 v58, 16, v59
	v_and_b32_e32 v59, 0xffff0000, v59
	v_pk_add_f32 v[46:47], v[46:47], v[52:53]
	v_pk_add_f32 v[44:45], v[44:45], v[60:61]
	v_pk_add_f32 v[42:43], v[42:43], v[54:55]
	v_pk_add_f32 v[40:41], v[40:41], v[62:63]
	v_pk_add_f32 v[38:39], v[38:39], v[56:57]
	v_pk_add_f32 v[36:37], v[36:37], v[64:65]
	v_pk_add_f32 v[52:53], v[34:35], v[58:59]
	v_pk_add_f32 v[54:55], v[32:33], v[66:67]
	v_cvt_pk_bf16_f32 v32, v44, v45
	v_cvt_pk_bf16_f32 v33, v46, v47
	v_mul_f32_e32 v34, v45, v45
	v_mul_f32_e32 v35, v47, v47
	v_mul_f32_e32 v45, v41, v41
	v_mul_f32_e32 v47, v43, v43
	v_mul_f32_e32 v56, v37, v37
	v_mul_f32_e32 v57, v39, v39
	v_mul_f32_e32 v58, v55, v55
	v_mul_f32_e32 v59, v53, v53
	v_fmac_f32_e32 v34, v44, v44
	v_fmac_f32_e32 v35, v46, v46
	v_fmac_f32_e32 v45, v40, v40
	v_fmac_f32_e32 v47, v42, v42
	v_fmac_f32_e32 v56, v36, v36
	v_fmac_f32_e32 v57, v38, v38
	v_fmac_f32_e32 v58, v54, v54
	v_fmac_f32_e32 v59, v52, v52
	v_add_f32_e32 v34, v34, v35
	v_add_f32_e32 v35, v45, v47
	v_add_f32_e32 v44, v56, v57
	v_add_f32_e32 v45, v58, v59
	v_add_f32_e32 v34, v34, v35
	v_add_f32_e32 v35, v44, v45
	v_add_f32_e32 v44, v34, v35
	ds_bpermute_b32 v45, v153, v44
	v_cvt_pk_bf16_f32 v34, v40, v41
	v_cvt_pk_bf16_f32 v35, v42, v43
	global_store_dwordx4 v[50:51], v[32:35], off sc1
	s_waitcnt lgkmcnt(0)
	s_nop 0
	v_add_f32_e32 v32, v44, v45
	ds_bpermute_b32 v33, v152, v32
	v_cvt_pk_bf16_f32 v34, v36, v37
	v_cvt_pk_bf16_f32 v35, v38, v39
	v_cvt_pk_bf16_f32 v36, v54, v55
	v_cvt_pk_bf16_f32 v37, v52, v53
	global_store_dwordx4 v[48:49], v[34:37], off offset:256 sc1
	s_and_saveexec_b64 s[0:1], s[2:3]
	s_cbranch_execz .LBB0_1370
	s_add_u32 s22, s43, s20
	s_addc_u32 s23, s44, s21
	s_waitcnt lgkmcnt(0)
	v_add_f32_e32 v34, v32, v33
	v_lshl_add_u64 v[32:33], v[134:135], 2, s[22:23]
	global_store_dword v[32:33], v34, off offset:576 sc1
; __device__ __forceinline__ unsigned pk2(float lo, float hi) { return pg8::cvt_pk_bf16(lo, hi); }
; __device__ __forceinline__ float bflo(unsigned w) { return __uint_as_float(w << 16); }
; __device__ __forceinline__ float bfhi(unsigned w) { return __uint_as_float(w & 0xffff0000u); }
;     __device__ __forceinline__ void operator()(const f32x4 (&acc)[2][2][4][2], const pg8::Unit& u, int wr, int wc, int fr, int fq) const {
;         const int row0 = u.pm * 256 + wr * 64 + fr; const int col0 = u.pn * 256 + wc * 32 + 8 * fq;
; #pragma unroll
;         for (int ai = 0; ai < 2; ++ai)
; #pragma unroll
;             for (int m = 0; m < 4; ++m) {
;                 const int r = row0 + ai * 128 + m * 16; float ss = 0.f;
; #pragma unroll
;                 for (int bj = 0; bj < 2; ++bj) {
;                     const size_t off = (size_t)r * DM + col0 + bj * 128;
;                     const u32x4 old = *(const u32x4*)(XB + off);
;                     const f32x4 x0 = (f32x4){bflo(old.x), bfhi(old.x), bflo(old.y), bfhi(old.y)} + acc[ai][bj][m][0];
;                     const f32x4 x1 = (f32x4){bflo(old.z), bfhi(old.z), bflo(old.w), bfhi(old.w)} + acc[ai][bj][m][1];
;                     u32x4 w; w.x = pk2(x0[0], x0[1]); w.y = pk2(x0[2], x0[3]); w.z = pk2(x1[0], x1[1]); w.w = pk2(x1[2], x1[3]); *(u32x4*)(XB + off) = w;
;                     ss += ((x0[0] * x0[0] + x0[1] * x0[1]) + (x0[2] * x0[2] + x0[3] * x0[3])) + ((x1[0] * x1[0] + x1[1] * x1[1]) + (x1[2] * x1[2] + x1[3] * x1[3]));
;                 }
;                 ss += __shfl_xor(ss, 16); ss += __shfl_xor(ss, 32);
;                 if (fq == 0) rowsq[(size_t)(u.pn * 4 + wc) * MTOK + r] = ss;
;             }
;     }
.LBB0_1370:
	s_or_b64 exec, exec, s[0:1]
	v_add_co_u32_e32 v34, vcc, 0xa0000, v136
	s_mov_b64 s[0:1], 0xa0000
	s_nop 0
	v_addc_co_u32_e32 v35, vcc, 0, v137, vcc
	s_waitcnt lgkmcnt(0)
	v_lshl_add_u64 v[32:33], v[136:137], 0, s[0:1]
	global_load_dwordx4 v[36:39], v[34:35], off
	global_load_dwordx4 v[40:43], v[32:33], off offset:256
	s_waitcnt vmcnt(1)
	v_lshlrev_b32_e32 v44, 16, v36
	v_and_b32_e32 v45, 0xffff0000, v36
	v_lshlrev_b32_e32 v36, 16, v37
	v_and_b32_e32 v37, 0xffff0000, v37
	v_lshlrev_b32_e32 v46, 16, v38
	v_and_b32_e32 v47, 0xffff0000, v38
	v_lshlrev_b32_e32 v38, 16, v39
	v_and_b32_e32 v39, 0xffff0000, v39
	s_waitcnt vmcnt(0)
	v_lshlrev_b32_e32 v48, 16, v40
	v_and_b32_e32 v49, 0xffff0000, v40
	v_lshlrev_b32_e32 v40, 16, v41
	v_and_b32_e32 v41, 0xffff0000, v41
	v_lshlrev_b32_e32 v50, 16, v42
	v_and_b32_e32 v51, 0xffff0000, v42
	v_lshlrev_b32_e32 v42, 16, v43
	v_and_b32_e32 v43, 0xffff0000, v43
	v_pk_add_f32 v[30:31], v[30:31], v[36:37]
	v_pk_add_f32 v[28:29], v[28:29], v[44:45]
	v_pk_add_f32 v[26:27], v[26:27], v[38:39]
	v_pk_add_f32 v[24:25], v[24:25], v[46:47]
	v_pk_add_f32 v[22:23], v[22:23], v[40:41]
	v_pk_add_f32 v[20:21], v[20:21], v[48:49]
	v_pk_add_f32 v[36:37], v[18:19], v[42:43]
	v_pk_add_f32 v[38:39], v[16:17], v[50:51]
	v_cvt_pk_bf16_f32 v16, v28, v29
	v_cvt_pk_bf16_f32 v17, v30, v31
	v_mul_f32_e32 v18, v29, v29
	v_mul_f32_e32 v19, v31, v31
	v_mul_f32_e32 v29, v25, v25
	v_mul_f32_e32 v31, v27, v27
	v_mul_f32_e32 v40, v21, v21
	v_mul_f32_e32 v41, v23, v23
	v_mul_f32_e32 v42, v39, v39
	v_mul_f32_e32 v43, v37, v37
	v_fmac_f32_e32 v18, v28, v28
	v_fmac_f32_e32 v19, v30, v30
	v_fmac_f32_e32 v29, v24, v24
	v_fmac_f32_e32 v31, v26, v26
	v_fmac_f32_e32 v40, v20, v20
	v_fmac_f32_e32 v41, v22, v22
	v_fmac_f32_e32 v42, v38, v38
	v_fmac_f32_e32 v43, v36, v36
	v_add_f32_e32 v18, v18, v19
	v_add_f32_e32 v19, v29, v31
	v_add_f32_e32 v28, v40, v41
	v_add_f32_e32 v29, v42, v43
	v_add_f32_e32 v18, v18, v19
	v_add_f32_e32 v19, v28, v29
	v_add_f32_e32 v28, v18, v19
	ds_bpermute_b32 v29, v153, v28
	v_cvt_pk_bf16_f32 v18, v24, v25
	v_cvt_pk_bf16_f32 v19, v26, v27
	global_store_dwordx4 v[34:35], v[16:19], off sc1
	s_waitcnt lgkmcnt(0)
	s_nop 0
	v_add_f32_e32 v16, v28, v29
	ds_bpermute_b32 v17, v152, v16
	v_cvt_pk_bf16_f32 v18, v20, v21
	v_cvt_pk_bf16_f32 v19, v22, v23
	v_cvt_pk_bf16_f32 v20, v38, v39
	v_cvt_pk_bf16_f32 v21, v36, v37
	global_store_dwordx4 v[32:33], v[18:21], off offset:256 sc1
	s_and_saveexec_b64 s[0:1], s[2:3]
	s_cbranch_execz .LBB0_1372
	s_add_u32 s22, s43, s20
	s_addc_u32 s23, s44, s21
	s_waitcnt lgkmcnt(0)
	v_add_f32_e32 v18, v16, v17
	v_lshl_add_u64 v[16:17], v[134:135], 2, s[22:23]
	global_store_dword v[16:17], v18, off offset:640 sc1
.LBB0_1372:
	s_or_b64 exec, exec, s[0:1]
	v_add_co_u32_e32 v18, vcc, 0xb0000, v136
	s_mov_b64 s[0:1], 0xb0000
	s_nop 0
	v_addc_co_u32_e32 v19, vcc, 0, v137, vcc
	s_waitcnt lgkmcnt(0)
	v_lshl_add_u64 v[16:17], v[136:137], 0, s[0:1]
	global_load_dwordx4 v[20:23], v[18:19], off
	global_load_dwordx4 v[24:27], v[16:17], off offset:256
	s_waitcnt vmcnt(1)
	v_lshlrev_b32_e32 v28, 16, v20
	v_and_b32_e32 v29, 0xffff0000, v20
	v_lshlrev_b32_e32 v20, 16, v21
	v_and_b32_e32 v21, 0xffff0000, v21
	v_lshlrev_b32_e32 v30, 16, v22
	v_and_b32_e32 v31, 0xffff0000, v22
	v_lshlrev_b32_e32 v22, 16, v23
	v_and_b32_e32 v23, 0xffff0000, v23
	s_waitcnt vmcnt(0)
	v_lshlrev_b32_e32 v32, 16, v24
	v_and_b32_e32 v33, 0xffff0000, v24
	v_lshlrev_b32_e32 v24, 16, v25
	v_and_b32_e32 v25, 0xffff0000, v25
	v_lshlrev_b32_e32 v34, 16, v26
	v_and_b32_e32 v35, 0xffff0000, v26
	v_lshlrev_b32_e32 v26, 16, v27
	v_and_b32_e32 v27, 0xffff0000, v27
	v_pk_add_f32 v[14:15], v[14:15], v[20:21]
	v_pk_add_f32 v[12:13], v[12:13], v[28:29]
	v_pk_add_f32 v[10:11], v[10:11], v[22:23]
	v_pk_add_f32 v[8:9], v[8:9], v[30:31]
	v_pk_add_f32 v[6:7], v[6:7], v[24:25]
	v_pk_add_f32 v[4:5], v[4:5], v[32:33]
	v_pk_add_f32 v[20:21], v[2:3], v[26:27]
	v_pk_add_f32 v[22:23], v[0:1], v[34:35]
	v_cvt_pk_bf16_f32 v0, v12, v13
	v_cvt_pk_bf16_f32 v1, v14, v15
	v_mul_f32_e32 v2, v13, v13
	v_mul_f32_e32 v3, v15, v15
	v_mul_f32_e32 v13, v9, v9
	v_mul_f32_e32 v15, v11, v11
	v_mul_f32_e32 v24, v5, v5
	v_mul_f32_e32 v25, v7, v7
	v_mul_f32_e32 v26, v23, v23
	v_mul_f32_e32 v27, v21, v21
	v_fmac_f32_e32 v2, v12, v12
	v_fmac_f32_e32 v3, v14, v14
	v_fmac_f32_e32 v13, v8, v8
	v_fmac_f32_e32 v15, v10, v10
	v_fmac_f32_e32 v24, v4, v4
	v_fmac_f32_e32 v25, v6, v6
	v_fmac_f32_e32 v26, v22, v22
	v_fmac_f32_e32 v27, v20, v20
	v_add_f32_e32 v2, v2, v3
	v_add_f32_e32 v3, v13, v15
	v_add_f32_e32 v12, v24, v25
	v_add_f32_e32 v13, v26, v27
	v_add_f32_e32 v2, v2, v3
	v_add_f32_e32 v3, v12, v13
	v_add_f32_e32 v12, v2, v3
	ds_bpermute_b32 v13, v153, v12
	v_cvt_pk_bf16_f32 v2, v8, v9
	v_cvt_pk_bf16_f32 v3, v10, v11
	global_store_dwordx4 v[18:19], v[0:3], off sc1
	s_waitcnt lgkmcnt(0)
	s_nop 0
	v_add_f32_e32 v0, v12, v13
	ds_bpermute_b32 v1, v152, v0
	v_cvt_pk_bf16_f32 v2, v4, v5
	v_cvt_pk_bf16_f32 v3, v6, v7
	v_cvt_pk_bf16_f32 v4, v22, v23
	v_cvt_pk_bf16_f32 v5, v20, v21
	global_store_dwordx4 v[16:17], v[2:5], off offset:256 sc1
	s_and_saveexec_b64 s[0:1], s[2:3]
	s_cbranch_execz .LBB0_1374
	s_add_u32 s20, s43, s20
	s_addc_u32 s21, s44, s21
	s_waitcnt lgkmcnt(0)
	v_add_f32_e32 v2, v0, v1
	v_lshl_add_u64 v[0:1], v[134:135], 2, s[20:21]
	global_store_dword v[0:1], v2, off offset:704 sc1

.LBB0_1378:
	s_waitcnt vmcnt(0) lgkmcnt(0)
	s_waitcnt lgkmcnt(0)
	s_barrier
	v_mbcnt_lo_u32_b32 v0, -1, 0
	v_mbcnt_hi_u32_b32 v0, -1, v0
	s_nop 0
	v_cmp_eq_u32_e32 vcc, 0, v0
	s_and_b64 s[2:3], s[92:93], vcc
	s_and_saveexec_b64 s[0:1], s[2:3]
	s_cbranch_execz .LBB0_1392
	s_mov_b64 s[2:3], s[68:69]
	s_load_dwordx2 s[2:3], s[2:3], 0xd8
	s_mov_b64 s[4:5], exec
	s_nop 0
	s_waitcnt vmcnt(0) lgkmcnt(0)
	s_waitcnt vmcnt(0)
	v_mbcnt_lo_u32_b32 v0, s4, 0
	v_mbcnt_hi_u32_b32 v0, s5, v0
	v_cmp_eq_u32_e32 vcc, 0, v0
	s_and_saveexec_b64 s[6:7], vcc
	s_cbranch_execz .LBB0_1381
	s_bcnt1_i32_b64 s4, s[4:5]
	v_mov_b32_e32 v0, s4
	s_and_b32 s4, s76, 7
	s_lshl_b32 s4, s4, 6
	s_add_i32 s4, s4, 0x400
	s_add_u32 s4, s2, s4
	s_addc_u32 s5, s3, 0
	global_atomic_add v145, v0, s[4:5]

.LBB0_1450:
	s_waitcnt vmcnt(0) lgkmcnt(0)
	s_waitcnt vmcnt(0)
	s_barrier
	v_mbcnt_lo_u32_b32 v0, -1, 0
	v_mbcnt_hi_u32_b32 v0, -1, v0
	s_nop 0
	v_cmp_eq_u32_e32 vcc, 0, v0
	s_and_b64 s[2:3], s[92:93], vcc
	s_and_saveexec_b64 s[0:1], s[2:3]
	s_cbranch_execz .LBB0_1464
	s_mov_b64 s[2:3], s[68:69]
	s_load_dwordx2 s[2:3], s[2:3], 0xd8
	s_mov_b64 s[4:5], exec
	s_nop 0
	s_waitcnt lgkmcnt(0)
	s_waitcnt vmcnt(0)
	v_mbcnt_lo_u32_b32 v0, s4, 0
	v_mbcnt_hi_u32_b32 v0, s5, v0
	v_cmp_eq_u32_e32 vcc, 0, v0
	s_and_saveexec_b64 s[6:7], vcc
	s_cbranch_execz .LBB0_1453
	s_bcnt1_i32_b64 s4, s[4:5]
	v_mov_b32_e32 v0, s4
	s_and_b32 s4, s76, 7
	s_lshl_b32 s4, s4, 6
	s_add_i32 s4, s4, 0x400
	s_add_u32 s4, s2, s4
	s_addc_u32 s5, s3, 0
	global_atomic_add v145, v0, s[4:5]

; __device__ __forceinline__ unsigned pk2(float lo, float hi) { return pg8::cvt_pk_bf16(lo, hi); }
; __device__ __forceinline__ float bflo(unsigned w) { return __uint_as_float(w << 16); }
; __device__ __forceinline__ float bfhi(unsigned w) { return __uint_as_float(w & 0xffff0000u); }
;     __device__ __forceinline__ void operator()(const f32x4 (&acc)[2][2][4][2], const pg8::Unit& u, int wr, int wc, int fr, int fq) const {
;         const int row0 = u.pm * 256 + wr * 64 + fr; const int col0 = u.pn * 256 + wc * 32 + 8 * fq;
; #pragma unroll
;         for (int ai = 0; ai < 2; ++ai)
; #pragma unroll
;             for (int m = 0; m < 4; ++m) {
;                 const int r = row0 + ai * 128 + m * 16; float ss = 0.f;
; #pragma unroll
;                 for (int bj = 0; bj < 2; ++bj) {
;                     const size_t off = (size_t)r * DM + col0 + bj * 128;
;                     const u32x4 old = *(const u32x4*)(XB + off);
;                     const f32x4 x0 = (f32x4){bflo(old.x), bfhi(old.x), bflo(old.y), bfhi(old.y)} + acc[ai][bj][m][0];
;                     const f32x4 x1 = (f32x4){bflo(old.z), bfhi(old.z), bflo(old.w), bfhi(old.w)} + acc[ai][bj][m][1];
;                     u32x4 w; w.x = pk2(x0[0], x0[1]); w.y = pk2(x0[2], x0[3]); w.z = pk2(x1[0], x1[1]); w.w = pk2(x1[2], x1[3]); *(u32x4*)(XB + off) = w;
;                     ss += ((x0[0] * x0[0] + x0[1] * x0[1]) + (x0[2] * x0[2] + x0[3] * x0[3])) + ((x1[0] * x1[0] + x1[1] * x1[1]) + (x1[2] * x1[2] + x1[3] * x1[3]));
;                 }
;                 ss += __shfl_xor(ss, 16); ss += __shfl_xor(ss, 32);
;                 if (fq == 0) rowsq[(size_t)(u.pn * 4 + wc) * MTOK + r] = ss;
;             }
.LBB0_1490:
	v_lshl_add_u32 v134, s46, 8, v140
	v_ashrrev_i32_e32 v135, 31, v134
	v_lshl_or_b32 v138, s45, 8, v142
	v_lshlrev_b64 v[136:137], 12, v[134:135]
	v_ashrrev_i32_e32 v139, 31, v138
	v_lshl_add_u64 v[136:137], s[10:11], 0, v[136:137]
	v_lshl_add_u64 v[136:137], v[138:139], 1, v[136:137]
	global_load_dwordx4 v[154:157], v[136:137], off
	global_load_dwordx4 v[158:161], v[136:137], off offset:256
	v_xor_b32_e32 v150, 16, v170
	v_xor_b32_e32 v151, 32, v170
	v_cmp_lt_i32_e32 vcc, v150, v171
	s_lshl_b32 s0, s45, 2
	s_or_b32 s0, s0, s37
	v_cndmask_b32_e32 v150, v170, v150, vcc
	v_cmp_lt_i32_e32 vcc, v151, v171
	v_lshlrev_b32_e32 v153, 2, v150
	s_ashr_i32 s1, s0, 31
	v_cndmask_b32_e32 v151, v170, v151, vcc
	v_lshlrev_b32_e32 v152, 2, v151
	s_lshl_b64 s[16:17], s[0:1], 16
	s_waitcnt vmcnt(0)
	v_lshlrev_b32_e32 v150, 16, v154
	v_and_b32_e32 v151, 0xffff0000, v154
	v_lshlrev_b32_e32 v154, 16, v155
	v_and_b32_e32 v155, 0xffff0000, v155
	v_lshlrev_b32_e32 v162, 16, v156
	v_and_b32_e32 v163, 0xffff0000, v156
	v_lshlrev_b32_e32 v156, 16, v157
	v_and_b32_e32 v157, 0xffff0000, v157
	v_lshlrev_b32_e32 v164, 16, v158
	v_and_b32_e32 v165, 0xffff0000, v158
	v_lshlrev_b32_e32 v158, 16, v159
	v_and_b32_e32 v159, 0xffff0000, v159
	v_lshlrev_b32_e32 v188, 16, v160
	v_and_b32_e32 v189, 0xffff0000, v160
	v_lshlrev_b32_e32 v160, 16, v161
	v_and_b32_e32 v161, 0xffff0000, v161
	v_pk_add_f32 v[126:127], v[126:127], v[154:155]
	v_pk_add_f32 v[124:125], v[124:125], v[150:151]
	v_pk_add_f32 v[122:123], v[122:123], v[156:157]
	v_pk_add_f32 v[120:121], v[120:121], v[162:163]
	v_pk_add_f32 v[118:119], v[118:119], v[158:159]
	v_pk_add_f32 v[116:117], v[116:117], v[164:165]
	v_pk_add_f32 v[150:151], v[114:115], v[160:161]
	v_pk_add_f32 v[154:155], v[112:113], v[188:189]
	v_cvt_pk_bf16_f32 v112, v124, v125
	v_cvt_pk_bf16_f32 v113, v126, v127
	v_mul_f32_e32 v114, v125, v125
	v_mul_f32_e32 v115, v127, v127
	v_mul_f32_e32 v125, v121, v121
	v_mul_f32_e32 v127, v123, v123
	v_mul_f32_e32 v156, v117, v117
	v_mul_f32_e32 v157, v119, v119
	v_mul_f32_e32 v158, v155, v155
	v_mul_f32_e32 v159, v151, v151
	v_fmac_f32_e32 v114, v124, v124
	v_fmac_f32_e32 v115, v126, v126
	v_fmac_f32_e32 v125, v120, v120
	v_fmac_f32_e32 v127, v122, v122
	v_fmac_f32_e32 v156, v116, v116
	v_fmac_f32_e32 v157, v118, v118
	v_fmac_f32_e32 v158, v154, v154
	v_fmac_f32_e32 v159, v150, v150
	v_add_f32_e32 v114, v114, v115
	v_add_f32_e32 v115, v125, v127
	v_add_f32_e32 v124, v156, v157
	v_add_f32_e32 v125, v158, v159
	v_add_f32_e32 v114, v114, v115
	v_add_f32_e32 v115, v124, v125
	v_add_f32_e32 v124, v114, v115
	ds_bpermute_b32 v125, v153, v124
	v_cvt_pk_bf16_f32 v114, v120, v121
	v_cvt_pk_bf16_f32 v115, v122, v123
	global_store_dwordx4 v[136:137], v[112:115], off sc1
	s_waitcnt lgkmcnt(0)
	s_nop 0
	v_add_f32_e32 v112, v124, v125
	ds_bpermute_b32 v113, v152, v112
	v_cvt_pk_bf16_f32 v114, v116, v117
	v_cvt_pk_bf16_f32 v115, v118, v119
	v_cvt_pk_bf16_f32 v116, v154, v155
	v_cvt_pk_bf16_f32 v117, v150, v151
	global_store_dwordx4 v[136:137], v[114:117], off offset:256 sc1
	s_and_saveexec_b64 s[0:1], s[2:3]
	s_cbranch_execz .LBB0_1492
	s_add_u32 s18, s35, s16
	s_addc_u32 s19, s36, s17
	s_waitcnt lgkmcnt(0)
	v_add_f32_e32 v114, v112, v113
	v_lshl_add_u64 v[112:113], v[134:135], 2, s[18:19]
	global_store_dword v[112:113], v114, off sc1
.LBB0_1492:
	s_or_b64 exec, exec, s[0:1]
	v_or_b32_e32 v112, 16, v134
	s_waitcnt lgkmcnt(0)
	v_ashrrev_i32_e32 v113, 31, v112
	v_lshlrev_b64 v[112:113], 12, v[112:113]
	v_lshl_add_u64 v[112:113], s[10:11], 0, v[112:113]
	v_lshl_add_u64 v[112:113], v[138:139], 1, v[112:113]
	global_load_dwordx4 v[114:117], v[112:113], off
	global_load_dwordx4 v[118:121], v[112:113], off offset:256
	s_waitcnt vmcnt(1)
	v_lshlrev_b32_e32 v122, 16, v114
	v_and_b32_e32 v123, 0xffff0000, v114
	v_lshlrev_b32_e32 v114, 16, v115
	v_and_b32_e32 v115, 0xffff0000, v115
	v_lshlrev_b32_e32 v124, 16, v116
	v_and_b32_e32 v125, 0xffff0000, v116
	v_lshlrev_b32_e32 v116, 16, v117
	v_and_b32_e32 v117, 0xffff0000, v117
	s_waitcnt vmcnt(0)
	v_lshlrev_b32_e32 v126, 16, v118
	v_and_b32_e32 v127, 0xffff0000, v118
	v_lshlrev_b32_e32 v118, 16, v119
	v_and_b32_e32 v119, 0xffff0000, v119
	v_lshlrev_b32_e32 v150, 16, v120
	v_and_b32_e32 v151, 0xffff0000, v120
	v_lshlrev_b32_e32 v120, 16, v121
	v_and_b32_e32 v121, 0xffff0000, v121
	v_pk_add_f32 v[110:111], v[110:111], v[114:115]
	v_pk_add_f32 v[108:109], v[108:109], v[122:123]
	v_pk_add_f32 v[106:107], v[106:107], v[116:117]
	v_pk_add_f32 v[104:105], v[104:105], v[124:125]
	v_pk_add_f32 v[102:103], v[102:103], v[118:119]
	v_pk_add_f32 v[100:101], v[100:101], v[126:127]
	v_pk_add_f32 v[114:115], v[98:99], v[120:121]
	v_pk_add_f32 v[116:117], v[96:97], v[150:151]
	v_cvt_pk_bf16_f32 v96, v108, v109
	v_cvt_pk_bf16_f32 v97, v110, v111
	v_mul_f32_e32 v98, v109, v109
	v_mul_f32_e32 v99, v111, v111
	v_mul_f32_e32 v109, v105, v105
	v_mul_f32_e32 v111, v107, v107
	v_mul_f32_e32 v118, v101, v101
	v_mul_f32_e32 v119, v103, v103
	v_mul_f32_e32 v120, v117, v117
	v_mul_f32_e32 v121, v115, v115
	v_fmac_f32_e32 v98, v108, v108
	v_fmac_f32_e32 v99, v110, v110
	v_fmac_f32_e32 v109, v104, v104
	v_fmac_f32_e32 v111, v106, v106
	v_fmac_f32_e32 v118, v100, v100
	v_fmac_f32_e32 v119, v102, v102
	v_fmac_f32_e32 v120, v116, v116
	v_fmac_f32_e32 v121, v114, v114
	v_add_f32_e32 v98, v98, v99
	v_add_f32_e32 v99, v109, v111
	v_add_f32_e32 v108, v118, v119
	v_add_f32_e32 v109, v120, v121
	v_add_f32_e32 v98, v98, v99
	v_add_f32_e32 v99, v108, v109
	v_add_f32_e32 v108, v98, v99
	ds_bpermute_b32 v109, v153, v108
	v_cvt_pk_bf16_f32 v98, v104, v105
	v_cvt_pk_bf16_f32 v99, v106, v107
	global_store_dwordx4 v[112:113], v[96:99], off sc1
	s_waitcnt lgkmcnt(0)
	s_nop 0
	v_add_f32_e32 v96, v108, v109
	ds_bpermute_b32 v97, v152, v96
	v_cvt_pk_bf16_f32 v98, v100, v101
	v_cvt_pk_bf16_f32 v99, v102, v103
	v_cvt_pk_bf16_f32 v100, v116, v117
	v_cvt_pk_bf16_f32 v101, v114, v115
	global_store_dwordx4 v[112:113], v[98:101], off offset:256 sc1
	s_and_saveexec_b64 s[0:1], s[2:3]
	s_cbranch_execz .LBB0_1494
	s_add_u32 s18, s35, s16
	s_addc_u32 s19, s36, s17
	s_waitcnt lgkmcnt(0)
	v_add_f32_e32 v98, v96, v97
	v_lshl_add_u64 v[96:97], v[134:135], 2, s[18:19]
	global_store_dword v[96:97], v98, off offset:64 sc1
; __device__ __forceinline__ unsigned pk2(float lo, float hi) { return pg8::cvt_pk_bf16(lo, hi); }
; __device__ __forceinline__ float bflo(unsigned w) { return __uint_as_float(w << 16); }
; __device__ __forceinline__ float bfhi(unsigned w) { return __uint_as_float(w & 0xffff0000u); }
;     __device__ __forceinline__ void operator()(const f32x4 (&acc)[2][2][4][2], const pg8::Unit& u, int wr, int wc, int fr, int fq) const {
;         const int row0 = u.pm * 256 + wr * 64 + fr; const int col0 = u.pn * 256 + wc * 32 + 8 * fq;
; #pragma unroll
;         for (int ai = 0; ai < 2; ++ai)
; #pragma unroll
;             for (int m = 0; m < 4; ++m) {
;                 const int r = row0 + ai * 128 + m * 16; float ss = 0.f;
; #pragma unroll
;                 for (int bj = 0; bj < 2; ++bj) {
;                     const size_t off = (size_t)r * DM + col0 + bj * 128;
;                     const u32x4 old = *(const u32x4*)(XB + off);
;                     const f32x4 x0 = (f32x4){bflo(old.x), bfhi(old.x), bflo(old.y), bfhi(old.y)} + acc[ai][bj][m][0];
;                     const f32x4 x1 = (f32x4){bflo(old.z), bfhi(old.z), bflo(old.w), bfhi(old.w)} + acc[ai][bj][m][1];
;                     u32x4 w; w.x = pk2(x0[0], x0[1]); w.y = pk2(x0[2], x0[3]); w.z = pk2(x1[0], x1[1]); w.w = pk2(x1[2], x1[3]); *(u32x4*)(XB + off) = w;
;                     ss += ((x0[0] * x0[0] + x0[1] * x0[1]) + (x0[2] * x0[2] + x0[3] * x0[3])) + ((x1[0] * x1[0] + x1[1] * x1[1]) + (x1[2] * x1[2] + x1[3] * x1[3]));
;                 }
;                 ss += __shfl_xor(ss, 16); ss += __shfl_xor(ss, 32);
;                 if (fq == 0) rowsq[(size_t)(u.pn * 4 + wc) * MTOK + r] = ss;
;             }
.LBB0_1494:
	s_or_b64 exec, exec, s[0:1]
	v_or_b32_e32 v96, 32, v134
	s_waitcnt lgkmcnt(0)
	v_ashrrev_i32_e32 v97, 31, v96
	v_lshlrev_b64 v[96:97], 12, v[96:97]
	v_lshl_add_u64 v[96:97], s[10:11], 0, v[96:97]
	v_lshl_add_u64 v[96:97], v[138:139], 1, v[96:97]
	global_load_dwordx4 v[98:101], v[96:97], off
	global_load_dwordx4 v[102:105], v[96:97], off offset:256
	s_waitcnt vmcnt(1)
	v_lshlrev_b32_e32 v106, 16, v98
	v_and_b32_e32 v107, 0xffff0000, v98
	v_lshlrev_b32_e32 v98, 16, v99
	v_and_b32_e32 v99, 0xffff0000, v99
	v_lshlrev_b32_e32 v108, 16, v100
	v_and_b32_e32 v109, 0xffff0000, v100
	v_lshlrev_b32_e32 v100, 16, v101
	v_and_b32_e32 v101, 0xffff0000, v101
	s_waitcnt vmcnt(0)
	v_lshlrev_b32_e32 v110, 16, v102
	v_and_b32_e32 v111, 0xffff0000, v102
	v_lshlrev_b32_e32 v102, 16, v103
	v_and_b32_e32 v103, 0xffff0000, v103
	v_lshlrev_b32_e32 v112, 16, v104
	v_and_b32_e32 v113, 0xffff0000, v104
	v_lshlrev_b32_e32 v104, 16, v105
	v_and_b32_e32 v105, 0xffff0000, v105
	v_pk_add_f32 v[94:95], v[94:95], v[98:99]
	v_pk_add_f32 v[92:93], v[92:93], v[106:107]
	v_pk_add_f32 v[90:91], v[90:91], v[100:101]
	v_pk_add_f32 v[88:89], v[88:89], v[108:109]
	v_pk_add_f32 v[86:87], v[86:87], v[102:103]
	v_pk_add_f32 v[84:85], v[84:85], v[110:111]
	v_pk_add_f32 v[98:99], v[82:83], v[104:105]
	v_pk_add_f32 v[100:101], v[80:81], v[112:113]
	v_cvt_pk_bf16_f32 v80, v92, v93
	v_cvt_pk_bf16_f32 v81, v94, v95
	v_mul_f32_e32 v82, v93, v93
	v_mul_f32_e32 v83, v95, v95
	v_mul_f32_e32 v93, v89, v89
	v_mul_f32_e32 v95, v91, v91
	v_mul_f32_e32 v102, v85, v85
	v_mul_f32_e32 v103, v87, v87
	v_mul_f32_e32 v104, v101, v101
	v_mul_f32_e32 v105, v99, v99
	v_fmac_f32_e32 v82, v92, v92
	v_fmac_f32_e32 v83, v94, v94
	v_fmac_f32_e32 v93, v88, v88
	v_fmac_f32_e32 v95, v90, v90
	v_fmac_f32_e32 v102, v84, v84
	v_fmac_f32_e32 v103, v86, v86
	v_fmac_f32_e32 v104, v100, v100
	v_fmac_f32_e32 v105, v98, v98
	v_add_f32_e32 v82, v82, v83
	v_add_f32_e32 v83, v93, v95
	v_add_f32_e32 v92, v102, v103
	v_add_f32_e32 v93, v104, v105
	v_add_f32_e32 v82, v82, v83
	v_add_f32_e32 v83, v92, v93
	v_add_f32_e32 v92, v82, v83
	ds_bpermute_b32 v93, v153, v92
	v_cvt_pk_bf16_f32 v82, v88, v89
	v_cvt_pk_bf16_f32 v83, v90, v91
	global_store_dwordx4 v[96:97], v[80:83], off sc1
	s_waitcnt lgkmcnt(0)
	s_nop 0
	v_add_f32_e32 v80, v92, v93
	ds_bpermute_b32 v81, v152, v80
	v_cvt_pk_bf16_f32 v82, v84, v85
	v_cvt_pk_bf16_f32 v83, v86, v87
	v_cvt_pk_bf16_f32 v84, v100, v101
	v_cvt_pk_bf16_f32 v85, v98, v99
	global_store_dwordx4 v[96:97], v[82:85], off offset:256 sc1
	s_and_saveexec_b64 s[0:1], s[2:3]
	s_cbranch_execz .LBB0_1496
	s_add_u32 s18, s35, s16
	s_addc_u32 s19, s36, s17
	s_waitcnt lgkmcnt(0)
	v_add_f32_e32 v82, v80, v81
	v_lshl_add_u64 v[80:81], v[134:135], 2, s[18:19]
	global_store_dword v[80:81], v82, off offset:128 sc1
.LBB0_1496:
	s_or_b64 exec, exec, s[0:1]
	v_or_b32_e32 v80, 48, v134
	s_waitcnt lgkmcnt(0)
	v_ashrrev_i32_e32 v81, 31, v80
	v_lshlrev_b64 v[80:81], 12, v[80:81]
	v_lshl_add_u64 v[80:81], s[10:11], 0, v[80:81]
	v_lshl_add_u64 v[80:81], v[138:139], 1, v[80:81]
	global_load_dwordx4 v[82:85], v[80:81], off
	global_load_dwordx4 v[86:89], v[80:81], off offset:256
	s_waitcnt vmcnt(1)
	v_lshlrev_b32_e32 v90, 16, v82
	v_and_b32_e32 v91, 0xffff0000, v82
	v_lshlrev_b32_e32 v82, 16, v83
	v_and_b32_e32 v83, 0xffff0000, v83
	v_lshlrev_b32_e32 v92, 16, v84
	v_and_b32_e32 v93, 0xffff0000, v84
	v_lshlrev_b32_e32 v84, 16, v85
	v_and_b32_e32 v85, 0xffff0000, v85
	s_waitcnt vmcnt(0)
	v_lshlrev_b32_e32 v94, 16, v86
	v_and_b32_e32 v95, 0xffff0000, v86
	v_lshlrev_b32_e32 v86, 16, v87
	v_and_b32_e32 v87, 0xffff0000, v87
	v_lshlrev_b32_e32 v96, 16, v88
	v_and_b32_e32 v97, 0xffff0000, v88
	v_lshlrev_b32_e32 v88, 16, v89
	v_and_b32_e32 v89, 0xffff0000, v89
	v_pk_add_f32 v[78:79], v[78:79], v[82:83]
	v_pk_add_f32 v[76:77], v[76:77], v[90:91]
	v_pk_add_f32 v[74:75], v[74:75], v[84:85]
	v_pk_add_f32 v[72:73], v[72:73], v[92:93]
	v_pk_add_f32 v[70:71], v[70:71], v[86:87]
	v_pk_add_f32 v[68:69], v[68:69], v[94:95]
	v_pk_add_f32 v[82:83], v[66:67], v[88:89]
	v_pk_add_f32 v[84:85], v[64:65], v[96:97]
	v_cvt_pk_bf16_f32 v64, v76, v77
	v_cvt_pk_bf16_f32 v65, v78, v79
	v_mul_f32_e32 v66, v77, v77
	v_mul_f32_e32 v67, v79, v79
	v_mul_f32_e32 v77, v73, v73
	v_mul_f32_e32 v79, v75, v75
	v_mul_f32_e32 v86, v69, v69
	v_mul_f32_e32 v87, v71, v71
	v_mul_f32_e32 v88, v85, v85
	v_mul_f32_e32 v89, v83, v83
	v_fmac_f32_e32 v66, v76, v76
	v_fmac_f32_e32 v67, v78, v78
	v_fmac_f32_e32 v77, v72, v72
	v_fmac_f32_e32 v79, v74, v74
	v_fmac_f32_e32 v86, v68, v68
	v_fmac_f32_e32 v87, v70, v70
	v_fmac_f32_e32 v88, v84, v84
	v_fmac_f32_e32 v89, v82, v82
	v_add_f32_e32 v66, v66, v67
	v_add_f32_e32 v67, v77, v79
	v_add_f32_e32 v76, v86, v87
	v_add_f32_e32 v77, v88, v89
	v_add_f32_e32 v66, v66, v67
	v_add_f32_e32 v67, v76, v77
	v_add_f32_e32 v76, v66, v67
	ds_bpermute_b32 v77, v153, v76
	v_cvt_pk_bf16_f32 v66, v72, v73
	v_cvt_pk_bf16_f32 v67, v74, v75
	global_store_dwordx4 v[80:81], v[64:67], off sc1
	s_waitcnt lgkmcnt(0)
	s_nop 0
	v_add_f32_e32 v64, v76, v77
	ds_bpermute_b32 v65, v152, v64
	v_cvt_pk_bf16_f32 v66, v68, v69
	v_cvt_pk_bf16_f32 v67, v70, v71
	v_cvt_pk_bf16_f32 v68, v84, v85
	v_cvt_pk_bf16_f32 v69, v82, v83
	global_store_dwordx4 v[80:81], v[66:69], off offset:256 sc1
	s_and_saveexec_b64 s[0:1], s[2:3]
	s_cbranch_execz .LBB0_1498
	s_add_u32 s18, s35, s16
	s_addc_u32 s19, s36, s17
	s_waitcnt lgkmcnt(0)
	v_add_f32_e32 v66, v64, v65
	v_lshl_add_u64 v[64:65], v[134:135], 2, s[18:19]
	global_store_dword v[64:65], v66, off offset:192 sc1
; __device__ __forceinline__ unsigned pk2(float lo, float hi) { return pg8::cvt_pk_bf16(lo, hi); }
; __device__ __forceinline__ float bflo(unsigned w) { return __uint_as_float(w << 16); }
; __device__ __forceinline__ float bfhi(unsigned w) { return __uint_as_float(w & 0xffff0000u); }
;     __device__ __forceinline__ void operator()(const f32x4 (&acc)[2][2][4][2], const pg8::Unit& u, int wr, int wc, int fr, int fq) const {
;         const int row0 = u.pm * 256 + wr * 64 + fr; const int col0 = u.pn * 256 + wc * 32 + 8 * fq;
; #pragma unroll
;         for (int ai = 0; ai < 2; ++ai)
; #pragma unroll
;             for (int m = 0; m < 4; ++m) {
;                 const int r = row0 + ai * 128 + m * 16; float ss = 0.f;
; #pragma unroll
;                 for (int bj = 0; bj < 2; ++bj) {
;                     const size_t off = (size_t)r * DM + col0 + bj * 128;
;                     const u32x4 old = *(const u32x4*)(XB + off);
;                     const f32x4 x0 = (f32x4){bflo(old.x), bfhi(old.x), bflo(old.y), bfhi(old.y)} + acc[ai][bj][m][0];
;                     const f32x4 x1 = (f32x4){bflo(old.z), bfhi(old.z), bflo(old.w), bfhi(old.w)} + acc[ai][bj][m][1];
;                     u32x4 w; w.x = pk2(x0[0], x0[1]); w.y = pk2(x0[2], x0[3]); w.z = pk2(x1[0], x1[1]); w.w = pk2(x1[2], x1[3]); *(u32x4*)(XB + off) = w;
;                     ss += ((x0[0] * x0[0] + x0[1] * x0[1]) + (x0[2] * x0[2] + x0[3] * x0[3])) + ((x1[0] * x1[0] + x1[1] * x1[1]) + (x1[2] * x1[2] + x1[3] * x1[3]));
;                 }
;                 ss += __shfl_xor(ss, 16); ss += __shfl_xor(ss, 32);
;                 if (fq == 0) rowsq[(size_t)(u.pn * 4 + wc) * MTOK + r] = ss;
;             }
.LBB0_1498:
	s_or_b64 exec, exec, s[0:1]
	v_add_co_u32_e32 v66, vcc, 0x80000, v136
	s_waitcnt lgkmcnt(0)
	v_lshl_add_u64 v[64:65], v[136:137], 0, s[94:95]
	v_addc_co_u32_e32 v67, vcc, 0, v137, vcc
	global_load_dwordx4 v[68:71], v[66:67], off
	global_load_dwordx4 v[72:75], v[64:65], off offset:256
	s_waitcnt vmcnt(1)
	v_lshlrev_b32_e32 v76, 16, v68
	v_and_b32_e32 v77, 0xffff0000, v68
	v_lshlrev_b32_e32 v68, 16, v69
	v_and_b32_e32 v69, 0xffff0000, v69
	v_lshlrev_b32_e32 v78, 16, v70
	v_and_b32_e32 v79, 0xffff0000, v70
	v_lshlrev_b32_e32 v70, 16, v71
	v_and_b32_e32 v71, 0xffff0000, v71
	s_waitcnt vmcnt(0)
	v_lshlrev_b32_e32 v80, 16, v72
	v_and_b32_e32 v81, 0xffff0000, v72
	v_lshlrev_b32_e32 v72, 16, v73
	v_and_b32_e32 v73, 0xffff0000, v73
	v_lshlrev_b32_e32 v82, 16, v74
	v_and_b32_e32 v83, 0xffff0000, v74
	v_lshlrev_b32_e32 v74, 16, v75
	v_and_b32_e32 v75, 0xffff0000, v75
	v_pk_add_f32 v[62:63], v[62:63], v[68:69]
	v_pk_add_f32 v[60:61], v[60:61], v[76:77]
	v_pk_add_f32 v[58:59], v[58:59], v[70:71]
	v_pk_add_f32 v[56:57], v[56:57], v[78:79]
	v_pk_add_f32 v[54:55], v[54:55], v[72:73]
	v_pk_add_f32 v[52:53], v[52:53], v[80:81]
	v_pk_add_f32 v[68:69], v[50:51], v[74:75]
	v_pk_add_f32 v[70:71], v[48:49], v[82:83]
	v_cvt_pk_bf16_f32 v48, v60, v61
	v_cvt_pk_bf16_f32 v49, v62, v63
	v_mul_f32_e32 v50, v61, v61
	v_mul_f32_e32 v51, v63, v63
	v_mul_f32_e32 v61, v57, v57
	v_mul_f32_e32 v63, v59, v59
	v_mul_f32_e32 v72, v53, v53
	v_mul_f32_e32 v73, v55, v55
	v_mul_f32_e32 v74, v71, v71
	v_mul_f32_e32 v75, v69, v69
	v_fmac_f32_e32 v50, v60, v60
	v_fmac_f32_e32 v51, v62, v62
	v_fmac_f32_e32 v61, v56, v56
	v_fmac_f32_e32 v63, v58, v58
	v_fmac_f32_e32 v72, v52, v52
	v_fmac_f32_e32 v73, v54, v54
	v_fmac_f32_e32 v74, v70, v70
	v_fmac_f32_e32 v75, v68, v68
	v_add_f32_e32 v50, v50, v51
	v_add_f32_e32 v51, v61, v63
	v_add_f32_e32 v60, v72, v73
	v_add_f32_e32 v61, v74, v75
	v_add_f32_e32 v50, v50, v51
	v_add_f32_e32 v51, v60, v61
	v_add_f32_e32 v60, v50, v51
	ds_bpermute_b32 v61, v153, v60
	v_cvt_pk_bf16_f32 v50, v56, v57
	v_cvt_pk_bf16_f32 v51, v58, v59
	global_store_dwordx4 v[66:67], v[48:51], off sc1
	s_waitcnt lgkmcnt(0)
	s_nop 0
	v_add_f32_e32 v48, v60, v61
	ds_bpermute_b32 v49, v152, v48
	v_cvt_pk_bf16_f32 v50, v52, v53
	v_cvt_pk_bf16_f32 v51, v54, v55
	v_cvt_pk_bf16_f32 v52, v70, v71
	v_cvt_pk_bf16_f32 v53, v68, v69
	global_store_dwordx4 v[64:65], v[50:53], off offset:256 sc1
	s_and_saveexec_b64 s[0:1], s[2:3]
	s_cbranch_execz .LBB0_1500
	s_add_u32 s18, s35, s16
	s_addc_u32 s19, s36, s17
	s_waitcnt lgkmcnt(0)
	v_add_f32_e32 v50, v48, v49
	v_lshl_add_u64 v[48:49], v[134:135], 2, s[18:19]
	global_store_dword v[48:49], v50, off offset:512 sc1
.LBB0_1500:
	s_or_b64 exec, exec, s[0:1]
	v_add_co_u32_e32 v50, vcc, 0x90000, v136
	s_mov_b64 s[0:1], 0x90000
	s_nop 0
	v_addc_co_u32_e32 v51, vcc, 0, v137, vcc
	s_waitcnt lgkmcnt(0)
	v_lshl_add_u64 v[48:49], v[136:137], 0, s[0:1]
	global_load_dwordx4 v[52:55], v[50:51], off
	global_load_dwordx4 v[56:59], v[48:49], off offset:256
	s_waitcnt vmcnt(1)
	v_lshlrev_b32_e32 v60, 16, v52
	v_and_b32_e32 v61, 0xffff0000, v52
	v_lshlrev_b32_e32 v52, 16, v53
	v_and_b32_e32 v53, 0xffff0000, v53
	v_lshlrev_b32_e32 v62, 16, v54
	v_and_b32_e32 v63, 0xffff0000, v54
	v_lshlrev_b32_e32 v54, 16, v55
	v_and_b32_e32 v55, 0xffff0000, v55
	s_waitcnt vmcnt(0)
	v_lshlrev_b32_e32 v64, 16, v56
	v_and_b32_e32 v65, 0xffff0000, v56
	v_lshlrev_b32_e32 v56, 16, v57
	v_and_b32_e32 v57, 0xffff0000, v57
	v_lshlrev_b32_e32 v66, 16, v58
	v_and_b32_e32 v67, 0xffff0000, v58
	v_lshlrev_b32_e32 v58, 16, v59
	v_and_b32_e32 v59, 0xffff0000, v59
	v_pk_add_f32 v[46:47], v[46:47], v[52:53]
	v_pk_add_f32 v[44:45], v[44:45], v[60:61]
	v_pk_add_f32 v[42:43], v[42:43], v[54:55]
	v_pk_add_f32 v[40:41], v[40:41], v[62:63]
	v_pk_add_f32 v[38:39], v[38:39], v[56:57]
	v_pk_add_f32 v[36:37], v[36:37], v[64:65]
	v_pk_add_f32 v[52:53], v[34:35], v[58:59]
	v_pk_add_f32 v[54:55], v[32:33], v[66:67]
	v_cvt_pk_bf16_f32 v32, v44, v45
	v_cvt_pk_bf16_f32 v33, v46, v47
	v_mul_f32_e32 v34, v45, v45
	v_mul_f32_e32 v35, v47, v47
	v_mul_f32_e32 v45, v41, v41
	v_mul_f32_e32 v47, v43, v43
	v_mul_f32_e32 v56, v37, v37
	v_mul_f32_e32 v57, v39, v39
	v_mul_f32_e32 v58, v55, v55
	v_mul_f32_e32 v59, v53, v53
	v_fmac_f32_e32 v34, v44, v44
	v_fmac_f32_e32 v35, v46, v46
	v_fmac_f32_e32 v45, v40, v40
	v_fmac_f32_e32 v47, v42, v42
	v_fmac_f32_e32 v56, v36, v36
	v_fmac_f32_e32 v57, v38, v38
	v_fmac_f32_e32 v58, v54, v54
	v_fmac_f32_e32 v59, v52, v52
	v_add_f32_e32 v34, v34, v35
	v_add_f32_e32 v35, v45, v47
	v_add_f32_e32 v44, v56, v57
	v_add_f32_e32 v45, v58, v59
	v_add_f32_e32 v34, v34, v35
	v_add_f32_e32 v35, v44, v45
	v_add_f32_e32 v44, v34, v35
	ds_bpermute_b32 v45, v153, v44
	v_cvt_pk_bf16_f32 v34, v40, v41
	v_cvt_pk_bf16_f32 v35, v42, v43
	global_store_dwordx4 v[50:51], v[32:35], off sc1
	s_waitcnt lgkmcnt(0)
	s_nop 0
	v_add_f32_e32 v32, v44, v45
	ds_bpermute_b32 v33, v152, v32
	v_cvt_pk_bf16_f32 v34, v36, v37
	v_cvt_pk_bf16_f32 v35, v38, v39
	v_cvt_pk_bf16_f32 v36, v54, v55
	v_cvt_pk_bf16_f32 v37, v52, v53
	global_store_dwordx4 v[48:49], v[34:37], off offset:256 sc1
	s_and_saveexec_b64 s[0:1], s[2:3]
	s_cbranch_execz .LBB0_1502
	s_add_u32 s18, s35, s16
	s_addc_u32 s19, s36, s17
	s_waitcnt lgkmcnt(0)
	v_add_f32_e32 v34, v32, v33
	v_lshl_add_u64 v[32:33], v[134:135], 2, s[18:19]
	global_store_dword v[32:33], v34, off offset:576 sc1
; __device__ __forceinline__ unsigned pk2(float lo, float hi) { return pg8::cvt_pk_bf16(lo, hi); }
; __device__ __forceinline__ float bflo(unsigned w) { return __uint_as_float(w << 16); }
; __device__ __forceinline__ float bfhi(unsigned w) { return __uint_as_float(w & 0xffff0000u); }
;     __device__ __forceinline__ void operator()(const f32x4 (&acc)[2][2][4][2], const pg8::Unit& u, int wr, int wc, int fr, int fq) const {
;         const int row0 = u.pm * 256 + wr * 64 + fr; const int col0 = u.pn * 256 + wc * 32 + 8 * fq;
; #pragma unroll
;         for (int ai = 0; ai < 2; ++ai)
; #pragma unroll
;             for (int m = 0; m < 4; ++m) {
;                 const int r = row0 + ai * 128 + m * 16; float ss = 0.f;
; #pragma unroll
;                 for (int bj = 0; bj < 2; ++bj) {
;                     const size_t off = (size_t)r * DM + col0 + bj * 128;
;                     const u32x4 old = *(const u32x4*)(XB + off);
;                     const f32x4 x0 = (f32x4){bflo(old.x), bfhi(old.x), bflo(old.y), bfhi(old.y)} + acc[ai][bj][m][0];
;                     const f32x4 x1 = (f32x4){bflo(old.z), bfhi(old.z), bflo(old.w), bfhi(old.w)} + acc[ai][bj][m][1];
;                     u32x4 w; w.x = pk2(x0[0], x0[1]); w.y = pk2(x0[2], x0[3]); w.z = pk2(x1[0], x1[1]); w.w = pk2(x1[2], x1[3]); *(u32x4*)(XB + off) = w;
;                     ss += ((x0[0] * x0[0] + x0[1] * x0[1]) + (x0[2] * x0[2] + x0[3] * x0[3])) + ((x1[0] * x1[0] + x1[1] * x1[1]) + (x1[2] * x1[2] + x1[3] * x1[3]));
;                 }
;                 ss += __shfl_xor(ss, 16); ss += __shfl_xor(ss, 32);
;                 if (fq == 0) rowsq[(size_t)(u.pn * 4 + wc) * MTOK + r] = ss;
;             }
.LBB0_1502:
	s_or_b64 exec, exec, s[0:1]
	v_add_co_u32_e32 v34, vcc, 0xa0000, v136
	s_mov_b64 s[0:1], 0xa0000
	s_nop 0
	v_addc_co_u32_e32 v35, vcc, 0, v137, vcc
	s_waitcnt lgkmcnt(0)
	v_lshl_add_u64 v[32:33], v[136:137], 0, s[0:1]
	global_load_dwordx4 v[36:39], v[34:35], off
	global_load_dwordx4 v[40:43], v[32:33], off offset:256
	s_waitcnt vmcnt(1)
	v_lshlrev_b32_e32 v44, 16, v36
	v_and_b32_e32 v45, 0xffff0000, v36
	v_lshlrev_b32_e32 v36, 16, v37
	v_and_b32_e32 v37, 0xffff0000, v37
	v_lshlrev_b32_e32 v46, 16, v38
	v_and_b32_e32 v47, 0xffff0000, v38
	v_lshlrev_b32_e32 v38, 16, v39
	v_and_b32_e32 v39, 0xffff0000, v39
	s_waitcnt vmcnt(0)
	v_lshlrev_b32_e32 v48, 16, v40
	v_and_b32_e32 v49, 0xffff0000, v40
	v_lshlrev_b32_e32 v40, 16, v41
	v_and_b32_e32 v41, 0xffff0000, v41
	v_lshlrev_b32_e32 v50, 16, v42
	v_and_b32_e32 v51, 0xffff0000, v42
	v_lshlrev_b32_e32 v42, 16, v43
	v_and_b32_e32 v43, 0xffff0000, v43
	v_pk_add_f32 v[30:31], v[30:31], v[36:37]
	v_pk_add_f32 v[28:29], v[28:29], v[44:45]
	v_pk_add_f32 v[26:27], v[26:27], v[38:39]
	v_pk_add_f32 v[24:25], v[24:25], v[46:47]
	v_pk_add_f32 v[22:23], v[22:23], v[40:41]
	v_pk_add_f32 v[20:21], v[20:21], v[48:49]
	v_pk_add_f32 v[36:37], v[18:19], v[42:43]
	v_pk_add_f32 v[38:39], v[16:17], v[50:51]
	v_cvt_pk_bf16_f32 v16, v28, v29
	v_cvt_pk_bf16_f32 v17, v30, v31
	v_mul_f32_e32 v18, v29, v29
	v_mul_f32_e32 v19, v31, v31
	v_mul_f32_e32 v29, v25, v25
	v_mul_f32_e32 v31, v27, v27
	v_mul_f32_e32 v40, v21, v21
	v_mul_f32_e32 v41, v23, v23
	v_mul_f32_e32 v42, v39, v39
	v_mul_f32_e32 v43, v37, v37
	v_fmac_f32_e32 v18, v28, v28
	v_fmac_f32_e32 v19, v30, v30
	v_fmac_f32_e32 v29, v24, v24
	v_fmac_f32_e32 v31, v26, v26
	v_fmac_f32_e32 v40, v20, v20
	v_fmac_f32_e32 v41, v22, v22
	v_fmac_f32_e32 v42, v38, v38
	v_fmac_f32_e32 v43, v36, v36
	v_add_f32_e32 v18, v18, v19
	v_add_f32_e32 v19, v29, v31
	v_add_f32_e32 v28, v40, v41
	v_add_f32_e32 v29, v42, v43
	v_add_f32_e32 v18, v18, v19
	v_add_f32_e32 v19, v28, v29
	v_add_f32_e32 v28, v18, v19
	ds_bpermute_b32 v29, v153, v28
	v_cvt_pk_bf16_f32 v18, v24, v25
	v_cvt_pk_bf16_f32 v19, v26, v27
	global_store_dwordx4 v[34:35], v[16:19], off sc1
	s_waitcnt lgkmcnt(0)
	s_nop 0
	v_add_f32_e32 v16, v28, v29
	ds_bpermute_b32 v17, v152, v16
	v_cvt_pk_bf16_f32 v18, v20, v21
	v_cvt_pk_bf16_f32 v19, v22, v23
	v_cvt_pk_bf16_f32 v20, v38, v39
	v_cvt_pk_bf16_f32 v21, v36, v37
	global_store_dwordx4 v[32:33], v[18:21], off offset:256 sc1
	s_and_saveexec_b64 s[0:1], s[2:3]
	s_cbranch_execz .LBB0_1504
	s_add_u32 s18, s35, s16
	s_addc_u32 s19, s36, s17
	s_waitcnt lgkmcnt(0)
	v_add_f32_e32 v18, v16, v17
	v_lshl_add_u64 v[16:17], v[134:135], 2, s[18:19]
	global_store_dword v[16:17], v18, off offset:640 sc1
.LBB0_1504:
	s_or_b64 exec, exec, s[0:1]
	v_add_co_u32_e32 v18, vcc, 0xb0000, v136
	s_mov_b64 s[0:1], 0xb0000
	s_nop 0
	v_addc_co_u32_e32 v19, vcc, 0, v137, vcc
	s_waitcnt lgkmcnt(0)
	v_lshl_add_u64 v[16:17], v[136:137], 0, s[0:1]
	global_load_dwordx4 v[20:23], v[18:19], off
	global_load_dwordx4 v[24:27], v[16:17], off offset:256
	s_waitcnt vmcnt(1)
	v_lshlrev_b32_e32 v28, 16, v20
	v_and_b32_e32 v29, 0xffff0000, v20
	v_lshlrev_b32_e32 v20, 16, v21
	v_and_b32_e32 v21, 0xffff0000, v21
	v_lshlrev_b32_e32 v30, 16, v22
	v_and_b32_e32 v31, 0xffff0000, v22
	v_lshlrev_b32_e32 v22, 16, v23
	v_and_b32_e32 v23, 0xffff0000, v23
	s_waitcnt vmcnt(0)
	v_lshlrev_b32_e32 v32, 16, v24
	v_and_b32_e32 v33, 0xffff0000, v24
	v_lshlrev_b32_e32 v24, 16, v25
	v_and_b32_e32 v25, 0xffff0000, v25
	v_lshlrev_b32_e32 v34, 16, v26
	v_and_b32_e32 v35, 0xffff0000, v26
	v_lshlrev_b32_e32 v26, 16, v27
	v_and_b32_e32 v27, 0xffff0000, v27
	v_pk_add_f32 v[14:15], v[14:15], v[20:21]
	v_pk_add_f32 v[12:13], v[12:13], v[28:29]
	v_pk_add_f32 v[10:11], v[10:11], v[22:23]
	v_pk_add_f32 v[8:9], v[8:9], v[30:31]
	v_pk_add_f32 v[6:7], v[6:7], v[24:25]
	v_pk_add_f32 v[4:5], v[4:5], v[32:33]
	v_pk_add_f32 v[20:21], v[2:3], v[26:27]
	v_pk_add_f32 v[22:23], v[0:1], v[34:35]
	v_cvt_pk_bf16_f32 v0, v12, v13
	v_cvt_pk_bf16_f32 v1, v14, v15
	v_mul_f32_e32 v2, v13, v13
	v_mul_f32_e32 v3, v15, v15
	v_mul_f32_e32 v13, v9, v9
	v_mul_f32_e32 v15, v11, v11
	v_mul_f32_e32 v24, v5, v5
	v_mul_f32_e32 v25, v7, v7
	v_mul_f32_e32 v26, v23, v23
	v_mul_f32_e32 v27, v21, v21
	v_fmac_f32_e32 v2, v12, v12
	v_fmac_f32_e32 v3, v14, v14
	v_fmac_f32_e32 v13, v8, v8
	v_fmac_f32_e32 v15, v10, v10
	v_fmac_f32_e32 v24, v4, v4
	v_fmac_f32_e32 v25, v6, v6
	v_fmac_f32_e32 v26, v22, v22
	v_fmac_f32_e32 v27, v20, v20
	v_add_f32_e32 v2, v2, v3
	v_add_f32_e32 v3, v13, v15
	v_add_f32_e32 v12, v24, v25
	v_add_f32_e32 v13, v26, v27
	v_add_f32_e32 v2, v2, v3
	v_add_f32_e32 v3, v12, v13
	v_add_f32_e32 v12, v2, v3
	ds_bpermute_b32 v13, v153, v12
	v_cvt_pk_bf16_f32 v2, v8, v9
	v_cvt_pk_bf16_f32 v3, v10, v11
	global_store_dwordx4 v[18:19], v[0:3], off sc1
	s_waitcnt lgkmcnt(0)
	s_nop 0
	v_add_f32_e32 v0, v12, v13
	ds_bpermute_b32 v1, v152, v0
	v_cvt_pk_bf16_f32 v2, v4, v5
	v_cvt_pk_bf16_f32 v3, v6, v7
	v_cvt_pk_bf16_f32 v4, v22, v23
	v_cvt_pk_bf16_f32 v5, v20, v21
	global_store_dwordx4 v[16:17], v[2:5], off offset:256 sc1
	s_and_saveexec_b64 s[0:1], s[2:3]
	s_cbranch_execz .LBB0_1506
	s_add_u32 s16, s35, s16
	s_addc_u32 s17, s36, s17
	s_waitcnt lgkmcnt(0)
	v_add_f32_e32 v2, v0, v1
	v_lshl_add_u64 v[0:1], v[134:135], 2, s[16:17]
	global_store_dword v[0:1], v2, off offset:704 sc1

.LBB0_1510:
	s_waitcnt vmcnt(0) lgkmcnt(0)
	s_waitcnt lgkmcnt(0)
	s_barrier
	v_readlane_b32 s0, v254, 1
	v_mbcnt_lo_u32_b32 v0, -1, 0
	v_mbcnt_hi_u32_b32 v0, -1, v0
	s_add_i32 s0, s0, 7
	v_cmp_eq_u32_e32 vcc, 0, v0
	s_and_b64 s[2:3], s[92:93], vcc
	v_writelane_b32 v254, s0, 1
	s_and_saveexec_b64 s[0:1], s[2:3]
	s_cbranch_execz .LBB0_347
	s_mov_b64 s[2:3], s[68:69]
	s_load_dwordx2 s[2:3], s[2:3], 0xd8
	s_mov_b64 s[4:5], exec
	v_readlane_b32 s7, v254, 1
	s_cmp_lg_u32 s7, 28
	s_cbranch_scc1 .Lnowb_7
	buffer_wbl2 sc1
